# filter output layer on f32 MFMA 4x4x1 (4 positions per wave, exact f32 fma chain), in1 rope epilogue loads pipelined, transposes loads batched
# speedup vs baseline: 1.1942x; 1.0278x over previous
; DI void hyena_filter_pos(const Params& p, int t, int w, int lane, float* sz, float* sh0, float* sh1) {
;   const float tn = (float)t / 4095.f;
;   const float wt = (6.283185307179586f * (float)t) / 4096.f;
;     ...
;   sh0[w * 64 + lane] = sinf(fr * a);
;   __syncthreads();
;   bf16_t* filt = (bf16_t*)(p.ws + OFF_FILT);
;   const float dmin = logf(1e-2f) / 1.5f, dmax = logf(1e-2f) / 0.3f;
; #pragma unroll 1
;   for (int i = 0; i < 16; ++i) {
;     int n = lane + 64 * i;
;     float o = 0.f;
; #pragma unroll 4
;     for (int k = 0; k < 64; ++k) o += sh0[w * 64 + k] * p.f_w4[k * 1024 + n];
.LBB0_45:
	s_andn2_saveexec_b64 s[6:7], s[14:15]
	v_mul_f32_e64 v6, |v2|, s63
	v_rndne_f32_e32 v8, v6
	v_cvt_i32_f32_e32 v6, v8
	v_fma_f32 v7, v8, s64, |v2|
	v_fmac_f32_e32 v7, 0xb3a22168, v8
	v_fmac_f32_e32 v7, 0xa7c234c4, v8
	s_or_b64 exec, exec, s[6:7]
	v_mul_f32_e32 v8, v7, v7
	v_fmamk_f32 v9, v8, 0xb94c1982, v65
	v_fmaak_f32 v9, v8, v9, 0xbe2aaa9d
	v_mul_f32_e32 v9, v8, v9
	v_fmac_f32_e32 v7, v7, v9
	v_fmamk_f32 v9, v8, 0x37d75334, v66
	v_fmaak_f32 v9, v8, v9, 0x3d2aabf7
	v_fmaak_f32 v9, v8, v9, 0xbf000004
	v_fma_f32 v8, v8, v9, 1.0
	v_and_b32_e32 v9, 1, v6
	v_lshlrev_b32_e32 v6, 30, v6
	v_cmp_eq_u32_e32 vcc, 0, v9
	v_and_b32_e32 v6, 0x80000000, v6
	v_xor_b32_e32 v3, v3, v2
	v_cndmask_b32_e32 v7, v8, v7, vcc
	v_xor_b32_e32 v3, v3, v6
	v_xor_b32_e32 v3, v3, v7
	v_cmp_class_f32_e64 vcc, v2, s67
	s_mov_b32 s14, 0
	v_cmp_eq_u32_e64 s[6:7], 0, v4
	v_cndmask_b32_e32 v2, v71, v3, vcc
	ds_write_b32 v51, v2 offset:640
	v_cmp_ne_u32_e64 s[8:9], 0, v4
	v_mov_b64_e32 v[2:3], v[40:41]
	s_waitcnt lgkmcnt(0)
	s_barrier
	v_bfe_u32 v148, v196, 6, 2
	v_sub_u32_e32 v149, v4, v148
	v_add_u32_e32 v232, 0, v149
	v_cvt_f32_u32_e32 v2, v232
	v_div_scale_f32 v3, s[6:7], s53, s53, v2
	v_rcp_f32_e32 v5, v3
	v_div_scale_f32 v6, vcc, v2, s53, v2
	v_fma_f32 v7, -v3, v5, 1.0
	v_fmac_f32_e32 v5, v7, v5
	v_mul_f32_e32 v7, v6, v5
	v_fma_f32 v8, -v3, v7, v6
	v_fmac_f32_e32 v7, v8, v5
	v_fma_f32 v3, -v3, v7, v6
	v_div_fmas_f32 v3, v3, v5, v7
	v_div_fixup_f32 v236, v3, s53, v2
	v_add_u32_e32 v233, 1, v149
	v_cvt_f32_u32_e32 v2, v233
	v_div_scale_f32 v3, s[6:7], s53, s53, v2
	v_rcp_f32_e32 v5, v3
	v_div_scale_f32 v6, vcc, v2, s53, v2
	v_fma_f32 v7, -v3, v5, 1.0
	v_fmac_f32_e32 v5, v7, v5
	v_mul_f32_e32 v7, v6, v5
	v_fma_f32 v8, -v3, v7, v6
	v_fmac_f32_e32 v7, v8, v5
	v_fma_f32 v3, -v3, v7, v6
	v_div_fmas_f32 v3, v3, v5, v7
	v_div_fixup_f32 v237, v3, s53, v2
	v_add_u32_e32 v234, 2, v149
	v_cvt_f32_u32_e32 v2, v234
	v_div_scale_f32 v3, s[6:7], s53, s53, v2
	v_rcp_f32_e32 v5, v3
	v_div_scale_f32 v6, vcc, v2, s53, v2
	v_fma_f32 v7, -v3, v5, 1.0
	v_fmac_f32_e32 v5, v7, v5
	v_mul_f32_e32 v7, v6, v5
	v_fma_f32 v8, -v3, v7, v6
	v_fmac_f32_e32 v7, v8, v5
	v_fma_f32 v3, -v3, v7, v6
	v_div_fmas_f32 v3, v3, v5, v7
	v_div_fixup_f32 v238, v3, s53, v2
	v_add_u32_e32 v235, 3, v149
	v_cvt_f32_u32_e32 v2, v235
	v_div_scale_f32 v3, s[6:7], s53, s53, v2
	v_rcp_f32_e32 v5, v3
	v_div_scale_f32 v6, vcc, v2, s53, v2
	v_fma_f32 v7, -v3, v5, 1.0
	v_fmac_f32_e32 v5, v7, v5
	v_mul_f32_e32 v7, v6, v5
	v_fma_f32 v8, -v3, v7, v6
	v_fmac_f32_e32 v7, v8, v5
	v_fma_f32 v3, -v3, v7, v6
	v_div_fmas_f32 v3, v3, v5, v7
	v_div_fixup_f32 v239, v3, s53, v2
	v_readfirstlane_b32 s80, v148
	v_readlane_b32 s70, v40, 0
	v_readlane_b32 s71, v41, 0
	s_nop 1
	s_lshl_b32 s80, s80, 2
	s_add_u32 s72, s70, 0x10000
	s_addc_u32 s73, s71, 0
	s_add_u32 s74, s72, 0x10000
	s_addc_u32 s75, s73, 0
	s_add_u32 s76, s74, 0x10000
	s_addc_u32 s77, s75, 0
	v_subrev_u32_e32 v151, s70, v40
	v_lshl_add_u32 v151, v148, 10, v151
	v_add_u32_e32 v152, 0x1000, v151
	v_add_u32_e32 v153, 0x2000, v151
	v_add_u32_e32 v154, 0x3000, v151
	v_add_u32_e32 v155, 0x4000, v151
	v_add_u32_e32 v156, 0x5000, v151
	v_add_u32_e32 v157, 0x6000, v151
	v_add_u32_e32 v158, 0x7000, v151
	v_add_u32_e32 v159, 0x8000, v151
	v_add_u32_e32 v160, 0x9000, v151
	v_add_u32_e32 v161, 0xa000, v151
	v_add_u32_e32 v162, 0xb000, v151
	v_add_u32_e32 v163, 0xc000, v151
	v_add_u32_e32 v164, 0xd000, v151
	v_add_u32_e32 v165, 0xe000, v151
	v_add_u32_e32 v166, 0xf000, v151
	v_lshlrev_b32_e32 v149, 8, v148
	v_sub_u32_e32 v149, v54, v149
	v_and_b32_e32 v2, 3, v1
	v_lshl_add_u32 v149, v2, 8, v149
	ds_read_b128 v[80:83], v149
	ds_read_b128 v[84:87], v149 offset:16
	ds_read_b128 v[88:91], v149 offset:32
	ds_read_b128 v[92:95], v149 offset:48
	ds_read_b128 v[96:99], v149 offset:64
	ds_read_b128 v[100:103], v149 offset:80
	ds_read_b128 v[104:107], v149 offset:96
	ds_read_b128 v[108:111], v149 offset:112
	ds_read_b128 v[112:115], v149 offset:128
	ds_read_b128 v[116:119], v149 offset:144
	ds_read_b128 v[120:123], v149 offset:160
	ds_read_b128 v[124:127], v149 offset:176
	ds_read_b128 v[128:131], v149 offset:192
	ds_read_b128 v[132:135], v149 offset:208
	ds_read_b128 v[136:139], v149 offset:224
	ds_read_b128 v[140:143], v149 offset:240
	global_load_dword v167, v151, s[70:71]
	global_load_dword v168, v152, s[70:71]
	global_load_dword v169, v153, s[70:71]
	global_load_dword v170, v154, s[70:71]
	global_load_dword v171, v155, s[70:71]
	global_load_dword v172, v156, s[70:71]
	global_load_dword v173, v157, s[70:71]
	global_load_dword v174, v158, s[70:71]
	global_load_dword v175, v159, s[70:71]
	global_load_dword v176, v160, s[70:71]
	global_load_dword v177, v161, s[70:71]
	global_load_dword v178, v162, s[70:71]
	global_load_dword v179, v163, s[70:71]
	global_load_dword v180, v164, s[70:71]
	global_load_dword v181, v165, s[70:71]
	global_load_dword v182, v166, s[70:71]
	global_load_dword v183, v151, s[72:73]
	global_load_dword v184, v152, s[72:73]
	global_load_dword v185, v153, s[72:73]
	global_load_dword v186, v154, s[72:73]
	global_load_dword v187, v155, s[72:73]
	global_load_dword v188, v156, s[72:73]
	global_load_dword v189, v157, s[72:73]
	global_load_dword v190, v158, s[72:73]
	global_load_dword v191, v159, s[72:73]
	global_load_dword v192, v160, s[72:73]
	global_load_dword v193, v161, s[72:73]
	global_load_dword v194, v162, s[72:73]
	global_load_dword v195, v163, s[72:73]
	global_load_dword v197, v164, s[72:73]
	global_load_dword v198, v165, s[72:73]
	global_load_dword v199, v166, s[72:73]
	global_load_dword v200, v151, s[74:75]
	global_load_dword v201, v152, s[74:75]
	global_load_dword v202, v153, s[74:75]
	global_load_dword v203, v154, s[74:75]
	global_load_dword v204, v155, s[74:75]
	global_load_dword v205, v156, s[74:75]
	global_load_dword v206, v157, s[74:75]
	global_load_dword v207, v158, s[74:75]
	global_load_dword v208, v159, s[74:75]
	global_load_dword v209, v160, s[74:75]
	global_load_dword v210, v161, s[74:75]
	global_load_dword v211, v162, s[74:75]
	global_load_dword v212, v163, s[74:75]
	global_load_dword v213, v164, s[74:75]
	global_load_dword v214, v165, s[74:75]
	global_load_dword v215, v166, s[74:75]
	global_load_dword v216, v151, s[76:77]
	global_load_dword v217, v152, s[76:77]
	global_load_dword v218, v153, s[76:77]
	global_load_dword v219, v154, s[76:77]
	global_load_dword v220, v155, s[76:77]
	global_load_dword v221, v156, s[76:77]
	global_load_dword v222, v157, s[76:77]
	global_load_dword v223, v158, s[76:77]
	global_load_dword v224, v159, s[76:77]
	global_load_dword v225, v160, s[76:77]
	global_load_dword v226, v161, s[76:77]
	global_load_dword v227, v162, s[76:77]
	global_load_dword v228, v163, s[76:77]
	global_load_dword v229, v164, s[76:77]
	global_load_dword v230, v165, s[76:77]
	global_load_dword v231, v166, s[76:77]
	s_mov_b32 s78, 0
	s_waitcnt lgkmcnt(0)
	s_branch .Lf_gi_loop

; DI void hyena_filter_pos(const Params& p, int t, int w, int lane, float* sz, float* sh0, float* sh1) {
;     ...
;   for (int i = 0; i < 16; ++i) {
;     int n = lane + 64 * i;
;     float o = 0.f;
; #pragma unroll 4
;     for (int k = 0; k < 64; ++k) o += sh0[w * 64 + k] * p.f_w4[k * 1024 + n];
.LBB0_49:
	s_add_u32 s79, s79, 1
	s_cmp_lt_u32 s79, 4
	s_cbranch_scc1 .Lf_p_loop
	s_add_u32 s78, s78, 1
	s_cmp_lt_u32 s78, 4
	s_cbranch_scc0 .LBB0_62
.Lf_gi_loop:
	v_mov_b32_e32 v144, 0
	v_mov_b32_e32 v145, 0
	v_mov_b32_e32 v146, 0
	v_mov_b32_e32 v147, 0
	s_cmp_eq_u32 s78, 3
	s_cbranch_scc1 .Lfilt_last
	s_waitcnt vmcnt(63)
	v_mfma_f32_4x4x1_16b_f32 v[144:147], v80, v167, v[144:147]
	global_load_dword v167, v151, s[70:71] offset:256
	s_waitcnt vmcnt(63)
	v_mfma_f32_4x4x1_16b_f32 v[144:147], v81, v168, v[144:147]
	global_load_dword v168, v152, s[70:71] offset:256
	s_waitcnt vmcnt(63)
	v_mfma_f32_4x4x1_16b_f32 v[144:147], v82, v169, v[144:147]
	global_load_dword v169, v153, s[70:71] offset:256
	s_waitcnt vmcnt(63)
	v_mfma_f32_4x4x1_16b_f32 v[144:147], v83, v170, v[144:147]
	global_load_dword v170, v154, s[70:71] offset:256
	s_waitcnt vmcnt(63)
	v_mfma_f32_4x4x1_16b_f32 v[144:147], v84, v171, v[144:147]
	global_load_dword v171, v155, s[70:71] offset:256
	s_waitcnt vmcnt(63)
	v_mfma_f32_4x4x1_16b_f32 v[144:147], v85, v172, v[144:147]
	global_load_dword v172, v156, s[70:71] offset:256
	s_waitcnt vmcnt(63)
	v_mfma_f32_4x4x1_16b_f32 v[144:147], v86, v173, v[144:147]
	global_load_dword v173, v157, s[70:71] offset:256
	s_waitcnt vmcnt(63)
	v_mfma_f32_4x4x1_16b_f32 v[144:147], v87, v174, v[144:147]
	global_load_dword v174, v158, s[70:71] offset:256
	s_waitcnt vmcnt(63)
	v_mfma_f32_4x4x1_16b_f32 v[144:147], v88, v175, v[144:147]
	global_load_dword v175, v159, s[70:71] offset:256
	s_waitcnt vmcnt(63)
	v_mfma_f32_4x4x1_16b_f32 v[144:147], v89, v176, v[144:147]
	global_load_dword v176, v160, s[70:71] offset:256
	s_waitcnt vmcnt(63)
	v_mfma_f32_4x4x1_16b_f32 v[144:147], v90, v177, v[144:147]
	global_load_dword v177, v161, s[70:71] offset:256
	s_waitcnt vmcnt(63)
	v_mfma_f32_4x4x1_16b_f32 v[144:147], v91, v178, v[144:147]
	global_load_dword v178, v162, s[70:71] offset:256
	s_waitcnt vmcnt(63)
	v_mfma_f32_4x4x1_16b_f32 v[144:147], v92, v179, v[144:147]
	global_load_dword v179, v163, s[70:71] offset:256
	s_waitcnt vmcnt(63)
	v_mfma_f32_4x4x1_16b_f32 v[144:147], v93, v180, v[144:147]
	global_load_dword v180, v164, s[70:71] offset:256
	s_waitcnt vmcnt(63)
	v_mfma_f32_4x4x1_16b_f32 v[144:147], v94, v181, v[144:147]
	global_load_dword v181, v165, s[70:71] offset:256
	s_waitcnt vmcnt(63)
	v_mfma_f32_4x4x1_16b_f32 v[144:147], v95, v182, v[144:147]
	global_load_dword v182, v166, s[70:71] offset:256
	s_waitcnt vmcnt(63)
	v_mfma_f32_4x4x1_16b_f32 v[144:147], v96, v183, v[144:147]
	global_load_dword v183, v151, s[72:73] offset:256
	s_waitcnt vmcnt(63)
	v_mfma_f32_4x4x1_16b_f32 v[144:147], v97, v184, v[144:147]
	global_load_dword v184, v152, s[72:73] offset:256
	s_waitcnt vmcnt(63)
	v_mfma_f32_4x4x1_16b_f32 v[144:147], v98, v185, v[144:147]
	global_load_dword v185, v153, s[72:73] offset:256
	s_waitcnt vmcnt(63)
	v_mfma_f32_4x4x1_16b_f32 v[144:147], v99, v186, v[144:147]
	global_load_dword v186, v154, s[72:73] offset:256
	s_waitcnt vmcnt(63)
	v_mfma_f32_4x4x1_16b_f32 v[144:147], v100, v187, v[144:147]
	global_load_dword v187, v155, s[72:73] offset:256
	s_waitcnt vmcnt(63)
	v_mfma_f32_4x4x1_16b_f32 v[144:147], v101, v188, v[144:147]
	global_load_dword v188, v156, s[72:73] offset:256
	s_waitcnt vmcnt(63)
	v_mfma_f32_4x4x1_16b_f32 v[144:147], v102, v189, v[144:147]
	global_load_dword v189, v157, s[72:73] offset:256
	s_waitcnt vmcnt(63)
	v_mfma_f32_4x4x1_16b_f32 v[144:147], v103, v190, v[144:147]
	global_load_dword v190, v158, s[72:73] offset:256
	s_waitcnt vmcnt(63)
	v_mfma_f32_4x4x1_16b_f32 v[144:147], v104, v191, v[144:147]
	global_load_dword v191, v159, s[72:73] offset:256
	s_waitcnt vmcnt(63)
	v_mfma_f32_4x4x1_16b_f32 v[144:147], v105, v192, v[144:147]
	global_load_dword v192, v160, s[72:73] offset:256
	s_waitcnt vmcnt(63)
	v_mfma_f32_4x4x1_16b_f32 v[144:147], v106, v193, v[144:147]
	global_load_dword v193, v161, s[72:73] offset:256
	s_waitcnt vmcnt(63)
	v_mfma_f32_4x4x1_16b_f32 v[144:147], v107, v194, v[144:147]
	global_load_dword v194, v162, s[72:73] offset:256
	s_waitcnt vmcnt(63)
	v_mfma_f32_4x4x1_16b_f32 v[144:147], v108, v195, v[144:147]
	global_load_dword v195, v163, s[72:73] offset:256
	s_waitcnt vmcnt(63)
	v_mfma_f32_4x4x1_16b_f32 v[144:147], v109, v197, v[144:147]
	global_load_dword v197, v164, s[72:73] offset:256
	s_waitcnt vmcnt(63)
	v_mfma_f32_4x4x1_16b_f32 v[144:147], v110, v198, v[144:147]
	global_load_dword v198, v165, s[72:73] offset:256
	s_waitcnt vmcnt(63)
	v_mfma_f32_4x4x1_16b_f32 v[144:147], v111, v199, v[144:147]
	global_load_dword v199, v166, s[72:73] offset:256
	s_waitcnt vmcnt(63)
	v_mfma_f32_4x4x1_16b_f32 v[144:147], v112, v200, v[144:147]
	global_load_dword v200, v151, s[74:75] offset:256
	s_waitcnt vmcnt(63)
	v_mfma_f32_4x4x1_16b_f32 v[144:147], v113, v201, v[144:147]
	global_load_dword v201, v152, s[74:75] offset:256
	s_waitcnt vmcnt(63)
	v_mfma_f32_4x4x1_16b_f32 v[144:147], v114, v202, v[144:147]
	global_load_dword v202, v153, s[74:75] offset:256
	s_waitcnt vmcnt(63)
	v_mfma_f32_4x4x1_16b_f32 v[144:147], v115, v203, v[144:147]
	global_load_dword v203, v154, s[74:75] offset:256
	s_waitcnt vmcnt(63)
	v_mfma_f32_4x4x1_16b_f32 v[144:147], v116, v204, v[144:147]
	global_load_dword v204, v155, s[74:75] offset:256
	s_waitcnt vmcnt(63)
	v_mfma_f32_4x4x1_16b_f32 v[144:147], v117, v205, v[144:147]
	global_load_dword v205, v156, s[74:75] offset:256
	s_waitcnt vmcnt(63)
	v_mfma_f32_4x4x1_16b_f32 v[144:147], v118, v206, v[144:147]
	global_load_dword v206, v157, s[74:75] offset:256
	s_waitcnt vmcnt(63)
	v_mfma_f32_4x4x1_16b_f32 v[144:147], v119, v207, v[144:147]
	global_load_dword v207, v158, s[74:75] offset:256
	s_waitcnt vmcnt(63)
; DI void hyena_filter_pos(const Params& p, int t, int w, int lane, float* sz, float* sh0, float* sh1) {
;     ...
;   for (int i = 0; i < 16; ++i) {
;     int n = lane + 64 * i;
;     float o = 0.f;
; #pragma unroll 4
;     for (int k = 0; k < 64; ++k) o += sh0[w * 64 + k] * p.f_w4[k * 1024 + n];
	v_mfma_f32_4x4x1_16b_f32 v[144:147], v120, v208, v[144:147]
	global_load_dword v208, v159, s[74:75] offset:256
	s_waitcnt vmcnt(63)
	v_mfma_f32_4x4x1_16b_f32 v[144:147], v121, v209, v[144:147]
	global_load_dword v209, v160, s[74:75] offset:256
	s_waitcnt vmcnt(63)
	v_mfma_f32_4x4x1_16b_f32 v[144:147], v122, v210, v[144:147]
	global_load_dword v210, v161, s[74:75] offset:256
	s_waitcnt vmcnt(63)
	v_mfma_f32_4x4x1_16b_f32 v[144:147], v123, v211, v[144:147]
	global_load_dword v211, v162, s[74:75] offset:256
	s_waitcnt vmcnt(63)
	v_mfma_f32_4x4x1_16b_f32 v[144:147], v124, v212, v[144:147]
	global_load_dword v212, v163, s[74:75] offset:256
	s_waitcnt vmcnt(63)
	v_mfma_f32_4x4x1_16b_f32 v[144:147], v125, v213, v[144:147]
	global_load_dword v213, v164, s[74:75] offset:256
	s_waitcnt vmcnt(63)
	v_mfma_f32_4x4x1_16b_f32 v[144:147], v126, v214, v[144:147]
	global_load_dword v214, v165, s[74:75] offset:256
	s_waitcnt vmcnt(63)
	v_mfma_f32_4x4x1_16b_f32 v[144:147], v127, v215, v[144:147]
	global_load_dword v215, v166, s[74:75] offset:256
	s_waitcnt vmcnt(63)
	v_mfma_f32_4x4x1_16b_f32 v[144:147], v128, v216, v[144:147]
	global_load_dword v216, v151, s[76:77] offset:256
	s_waitcnt vmcnt(63)
	v_mfma_f32_4x4x1_16b_f32 v[144:147], v129, v217, v[144:147]
	global_load_dword v217, v152, s[76:77] offset:256
	s_waitcnt vmcnt(63)
	v_mfma_f32_4x4x1_16b_f32 v[144:147], v130, v218, v[144:147]
	global_load_dword v218, v153, s[76:77] offset:256
	s_waitcnt vmcnt(63)
	v_mfma_f32_4x4x1_16b_f32 v[144:147], v131, v219, v[144:147]
	global_load_dword v219, v154, s[76:77] offset:256
	s_waitcnt vmcnt(63)
	v_mfma_f32_4x4x1_16b_f32 v[144:147], v132, v220, v[144:147]
	global_load_dword v220, v155, s[76:77] offset:256
	s_waitcnt vmcnt(63)
	v_mfma_f32_4x4x1_16b_f32 v[144:147], v133, v221, v[144:147]
	global_load_dword v221, v156, s[76:77] offset:256
	s_waitcnt vmcnt(63)
	v_mfma_f32_4x4x1_16b_f32 v[144:147], v134, v222, v[144:147]
	global_load_dword v222, v157, s[76:77] offset:256
	s_waitcnt vmcnt(63)
	v_mfma_f32_4x4x1_16b_f32 v[144:147], v135, v223, v[144:147]
	global_load_dword v223, v158, s[76:77] offset:256
	s_waitcnt vmcnt(63)
	v_mfma_f32_4x4x1_16b_f32 v[144:147], v136, v224, v[144:147]
	global_load_dword v224, v159, s[76:77] offset:256
	s_waitcnt vmcnt(63)
	v_mfma_f32_4x4x1_16b_f32 v[144:147], v137, v225, v[144:147]
	global_load_dword v225, v160, s[76:77] offset:256
	s_waitcnt vmcnt(63)
	v_mfma_f32_4x4x1_16b_f32 v[144:147], v138, v226, v[144:147]
	global_load_dword v226, v161, s[76:77] offset:256
	s_waitcnt vmcnt(63)
	v_mfma_f32_4x4x1_16b_f32 v[144:147], v139, v227, v[144:147]
	global_load_dword v227, v162, s[76:77] offset:256
	s_waitcnt vmcnt(63)
	v_mfma_f32_4x4x1_16b_f32 v[144:147], v140, v228, v[144:147]
	global_load_dword v228, v163, s[76:77] offset:256
	s_waitcnt vmcnt(63)
	v_mfma_f32_4x4x1_16b_f32 v[144:147], v141, v229, v[144:147]
	global_load_dword v229, v164, s[76:77] offset:256
	s_waitcnt vmcnt(63)
	v_mfma_f32_4x4x1_16b_f32 v[144:147], v142, v230, v[144:147]
	global_load_dword v230, v165, s[76:77] offset:256
	s_waitcnt vmcnt(63)
	v_mfma_f32_4x4x1_16b_f32 v[144:147], v143, v231, v[144:147]
	global_load_dword v231, v166, s[76:77] offset:256
	s_add_u32 s70, s70, 0x100
	s_addc_u32 s71, s71, 0
	s_add_u32 s72, s72, 0x100
	s_addc_u32 s73, s73, 0
	s_add_u32 s74, s74, 0x100
	s_addc_u32 s75, s75, 0
	s_add_u32 s76, s76, 0x100
	s_addc_u32 s77, s77, 0
	s_branch .Lfilt_epi
.Lfilt_last:
	s_waitcnt vmcnt(63)
	v_mfma_f32_4x4x1_16b_f32 v[144:147], v80, v167, v[144:147]
	s_nop 1
	s_waitcnt vmcnt(62)
	v_mfma_f32_4x4x1_16b_f32 v[144:147], v81, v168, v[144:147]
	s_nop 1
	s_waitcnt vmcnt(61)
	v_mfma_f32_4x4x1_16b_f32 v[144:147], v82, v169, v[144:147]
	s_nop 1
	s_waitcnt vmcnt(60)
	v_mfma_f32_4x4x1_16b_f32 v[144:147], v83, v170, v[144:147]
	s_nop 1
	s_waitcnt vmcnt(59)
	v_mfma_f32_4x4x1_16b_f32 v[144:147], v84, v171, v[144:147]
	s_nop 1
	s_waitcnt vmcnt(58)
	v_mfma_f32_4x4x1_16b_f32 v[144:147], v85, v172, v[144:147]
	s_nop 1
	s_waitcnt vmcnt(57)
	v_mfma_f32_4x4x1_16b_f32 v[144:147], v86, v173, v[144:147]
	s_nop 1
	s_waitcnt vmcnt(56)
	v_mfma_f32_4x4x1_16b_f32 v[144:147], v87, v174, v[144:147]
	s_nop 1
	s_waitcnt vmcnt(55)
	v_mfma_f32_4x4x1_16b_f32 v[144:147], v88, v175, v[144:147]
	s_nop 1
	s_waitcnt vmcnt(54)
	v_mfma_f32_4x4x1_16b_f32 v[144:147], v89, v176, v[144:147]
	s_nop 1
	s_waitcnt vmcnt(53)
	v_mfma_f32_4x4x1_16b_f32 v[144:147], v90, v177, v[144:147]
	s_nop 1
	s_waitcnt vmcnt(52)
	v_mfma_f32_4x4x1_16b_f32 v[144:147], v91, v178, v[144:147]
	s_nop 1
	s_waitcnt vmcnt(51)
	v_mfma_f32_4x4x1_16b_f32 v[144:147], v92, v179, v[144:147]
	s_nop 1
	s_waitcnt vmcnt(50)
	v_mfma_f32_4x4x1_16b_f32 v[144:147], v93, v180, v[144:147]
	s_nop 1
	s_waitcnt vmcnt(49)
	v_mfma_f32_4x4x1_16b_f32 v[144:147], v94, v181, v[144:147]
	s_nop 1
	s_waitcnt vmcnt(48)
	v_mfma_f32_4x4x1_16b_f32 v[144:147], v95, v182, v[144:147]
	s_nop 1
	s_waitcnt vmcnt(47)
	v_mfma_f32_4x4x1_16b_f32 v[144:147], v96, v183, v[144:147]
	s_nop 1
	s_waitcnt vmcnt(46)
	v_mfma_f32_4x4x1_16b_f32 v[144:147], v97, v184, v[144:147]
	s_nop 1
	s_waitcnt vmcnt(45)
	v_mfma_f32_4x4x1_16b_f32 v[144:147], v98, v185, v[144:147]
	s_nop 1
	s_waitcnt vmcnt(44)
	v_mfma_f32_4x4x1_16b_f32 v[144:147], v99, v186, v[144:147]
	s_nop 1
	s_waitcnt vmcnt(43)
	v_mfma_f32_4x4x1_16b_f32 v[144:147], v100, v187, v[144:147]
	s_nop 1
	s_waitcnt vmcnt(42)
	v_mfma_f32_4x4x1_16b_f32 v[144:147], v101, v188, v[144:147]
	s_nop 1
	s_waitcnt vmcnt(41)
	v_mfma_f32_4x4x1_16b_f32 v[144:147], v102, v189, v[144:147]
	s_nop 1
	s_waitcnt vmcnt(40)
; DI bf16_t f2bf(float x) { return (bf16_t)(pack2(x, 0.f) & 0xffffu); }
; DI void hyena_filter_pos(const Params& p, int t, int w, int lane, float* sz, float* sh0, float* sh1) {
;     ...
;     for (int k = 0; k < 64; ++k) o += sh0[w * 64 + k] * p.f_w4[k * 1024 + n];
;     int c = n & 511;
;     float delta = dmin + (float)c * ((dmax - dmin) / 511.f);
;     float win = expf(-tn * fabsf(delta));
;     o *= win;
;     if (n < 512) {
;       if (t == 0) o += p.hy_bias[c];
;       filt[(size_t)c * 8192 + 4096 + t] = f2bf(o);
;     } else {
;       if (t == 0) filt[(size_t)c * 8192] = 0;
;       else filt[(size_t)c * 8192 + 4096 - t] = f2bf(o);
	v_mfma_f32_4x4x1_16b_f32 v[144:147], v103, v190, v[144:147]
	s_nop 1
	s_waitcnt vmcnt(39)
	v_mfma_f32_4x4x1_16b_f32 v[144:147], v104, v191, v[144:147]
	s_nop 1
	s_waitcnt vmcnt(38)
	v_mfma_f32_4x4x1_16b_f32 v[144:147], v105, v192, v[144:147]
	s_nop 1
	s_waitcnt vmcnt(37)
	v_mfma_f32_4x4x1_16b_f32 v[144:147], v106, v193, v[144:147]
	s_nop 1
	s_waitcnt vmcnt(36)
	v_mfma_f32_4x4x1_16b_f32 v[144:147], v107, v194, v[144:147]
	s_nop 1
	s_waitcnt vmcnt(35)
	v_mfma_f32_4x4x1_16b_f32 v[144:147], v108, v195, v[144:147]
	s_nop 1
	s_waitcnt vmcnt(34)
	v_mfma_f32_4x4x1_16b_f32 v[144:147], v109, v197, v[144:147]
	s_nop 1
	s_waitcnt vmcnt(33)
	v_mfma_f32_4x4x1_16b_f32 v[144:147], v110, v198, v[144:147]
	s_nop 1
	s_waitcnt vmcnt(32)
	v_mfma_f32_4x4x1_16b_f32 v[144:147], v111, v199, v[144:147]
	s_nop 1
	s_waitcnt vmcnt(31)
	v_mfma_f32_4x4x1_16b_f32 v[144:147], v112, v200, v[144:147]
	s_nop 1
	s_waitcnt vmcnt(30)
	v_mfma_f32_4x4x1_16b_f32 v[144:147], v113, v201, v[144:147]
	s_nop 1
	s_waitcnt vmcnt(29)
	v_mfma_f32_4x4x1_16b_f32 v[144:147], v114, v202, v[144:147]
	s_nop 1
	s_waitcnt vmcnt(28)
	v_mfma_f32_4x4x1_16b_f32 v[144:147], v115, v203, v[144:147]
	s_nop 1
	s_waitcnt vmcnt(27)
	v_mfma_f32_4x4x1_16b_f32 v[144:147], v116, v204, v[144:147]
	s_nop 1
	s_waitcnt vmcnt(26)
	v_mfma_f32_4x4x1_16b_f32 v[144:147], v117, v205, v[144:147]
	s_nop 1
	s_waitcnt vmcnt(25)
	v_mfma_f32_4x4x1_16b_f32 v[144:147], v118, v206, v[144:147]
	s_nop 1
	s_waitcnt vmcnt(24)
	v_mfma_f32_4x4x1_16b_f32 v[144:147], v119, v207, v[144:147]
	s_nop 1
	s_waitcnt vmcnt(23)
	v_mfma_f32_4x4x1_16b_f32 v[144:147], v120, v208, v[144:147]
	s_nop 1
	s_waitcnt vmcnt(22)
	v_mfma_f32_4x4x1_16b_f32 v[144:147], v121, v209, v[144:147]
	s_nop 1
	s_waitcnt vmcnt(21)
	v_mfma_f32_4x4x1_16b_f32 v[144:147], v122, v210, v[144:147]
	s_nop 1
	s_waitcnt vmcnt(20)
	v_mfma_f32_4x4x1_16b_f32 v[144:147], v123, v211, v[144:147]
	s_nop 1
	s_waitcnt vmcnt(19)
	v_mfma_f32_4x4x1_16b_f32 v[144:147], v124, v212, v[144:147]
	s_nop 1
	s_waitcnt vmcnt(18)
	v_mfma_f32_4x4x1_16b_f32 v[144:147], v125, v213, v[144:147]
	s_nop 1
	s_waitcnt vmcnt(17)
	v_mfma_f32_4x4x1_16b_f32 v[144:147], v126, v214, v[144:147]
	s_nop 1
	s_waitcnt vmcnt(16)
	v_mfma_f32_4x4x1_16b_f32 v[144:147], v127, v215, v[144:147]
	s_nop 1
	s_waitcnt vmcnt(15)
	v_mfma_f32_4x4x1_16b_f32 v[144:147], v128, v216, v[144:147]
	s_nop 1
	s_waitcnt vmcnt(14)
	v_mfma_f32_4x4x1_16b_f32 v[144:147], v129, v217, v[144:147]
	s_nop 1
	s_waitcnt vmcnt(13)
	v_mfma_f32_4x4x1_16b_f32 v[144:147], v130, v218, v[144:147]
	s_nop 1
	s_waitcnt vmcnt(12)
	v_mfma_f32_4x4x1_16b_f32 v[144:147], v131, v219, v[144:147]
	s_nop 1
	s_waitcnt vmcnt(11)
	v_mfma_f32_4x4x1_16b_f32 v[144:147], v132, v220, v[144:147]
	s_nop 1
	s_waitcnt vmcnt(10)
	v_mfma_f32_4x4x1_16b_f32 v[144:147], v133, v221, v[144:147]
	s_nop 1
	s_waitcnt vmcnt(9)
	v_mfma_f32_4x4x1_16b_f32 v[144:147], v134, v222, v[144:147]
	s_nop 1
	s_waitcnt vmcnt(8)
	v_mfma_f32_4x4x1_16b_f32 v[144:147], v135, v223, v[144:147]
	s_nop 1
	s_waitcnt vmcnt(7)
	v_mfma_f32_4x4x1_16b_f32 v[144:147], v136, v224, v[144:147]
	s_nop 1
	s_waitcnt vmcnt(6)
	v_mfma_f32_4x4x1_16b_f32 v[144:147], v137, v225, v[144:147]
	s_nop 1
	s_waitcnt vmcnt(5)
	v_mfma_f32_4x4x1_16b_f32 v[144:147], v138, v226, v[144:147]
	s_nop 1
	s_waitcnt vmcnt(4)
	v_mfma_f32_4x4x1_16b_f32 v[144:147], v139, v227, v[144:147]
	s_nop 1
	s_waitcnt vmcnt(3)
	v_mfma_f32_4x4x1_16b_f32 v[144:147], v140, v228, v[144:147]
	s_nop 1
	s_waitcnt vmcnt(2)
	v_mfma_f32_4x4x1_16b_f32 v[144:147], v141, v229, v[144:147]
	s_nop 1
	s_waitcnt vmcnt(1)
	v_mfma_f32_4x4x1_16b_f32 v[144:147], v142, v230, v[144:147]
	s_nop 1
	s_waitcnt vmcnt(0)
	v_mfma_f32_4x4x1_16b_f32 v[144:147], v143, v231, v[144:147]
	s_nop 1
.Lfilt_epi:
	s_nop 4
	s_mov_b32 s79, 0
.Lf_p_loop:
	s_cmp_eq_u32 s79, 0
	s_cbranch_scc1 .Lf_sel0
	s_cmp_eq_u32 s79, 1
	s_cbranch_scc1 .Lf_sel1
	s_cmp_eq_u32 s79, 2
	s_cbranch_scc1 .Lf_sel2
	v_mov_b32_e32 v6, v147
	v_mov_b32_e32 v4, v235
	v_mov_b32_e32 v5, v239
	s_branch .Lf_seld
.Lf_sel0:
	v_mov_b32_e32 v6, v144
	v_mov_b32_e32 v4, v232
	v_mov_b32_e32 v5, v236
	s_branch .Lf_seld
.Lf_sel1:
	v_mov_b32_e32 v6, v145
	v_mov_b32_e32 v4, v233
	v_mov_b32_e32 v5, v237
	s_branch .Lf_seld
.Lf_sel2:
	v_mov_b32_e32 v6, v146
	v_mov_b32_e32 v4, v234
	v_mov_b32_e32 v5, v238
.Lf_seld:
	v_cmp_eq_u32_e64 s[6:7], 0, v4
	v_cmp_ne_u32_e64 s[8:9], 0, v4
	s_add_u32 s14, s80, s78
	s_lshl_b32 s15, s14, 6
	v_bitop3_b32 v7, s15, v72, v1 bitop3:0xc8
	v_cvt_f32_u32_e32 v8, v7
	s_mov_b32 s12, 0x3fb8aa3b
	s_cmp_gt_u32 s14, 7
	v_fmamk_f32 v8, v8, 0xbcc4df2d, v67
	v_mul_f32_e64 v8, |v8|, -v5
	v_mul_f32_e32 v9, 0x3fb8aa3b, v8
	v_fma_f32 v10, v8, s12, -v9
	v_rndne_f32_e32 v11, v9
	v_fmac_f32_e32 v10, 0x32a5705f, v8
	v_sub_f32_e32 v9, v9, v11
	v_add_f32_e32 v9, v9, v10
	v_cvt_i32_f32_e32 v11, v11
	v_exp_f32_e32 v9, v9
	s_mov_b32 s12, 0xc2ce8ed0
	v_cmp_ngt_f32_e32 vcc, s12, v8
	s_mov_b32 s12, 0x42b17218
	v_ldexp_f32 v9, v9, v11
	v_cndmask_b32_e32 v9, 0, v9, vcc
	v_cmp_nlt_f32_e32 vcc, s12, v8
	s_mov_b64 s[12:13], -1
	s_nop 0
	v_cndmask_b32_e32 v8, v73, v9, vcc
	v_mul_f32_e32 v6, v8, v6
	s_cbranch_scc0 .LBB0_58
	s_and_saveexec_b64 s[12:13], s[8:9]
	s_xor_b64 s[12:13], exec, s[12:13]
	s_cbranch_execz .LBB0_55
	v_lshlrev_b32_e32 v8, 13, v7
	v_sub_u32_e32 v8, v8, v4
	v_ashrrev_i32_e32 v9, 31, v8
	v_lshl_add_u64 v[8:9], v[8:9], 1, s[18:19]
	v_add_co_u32_e32 v8, vcc, 0x2000, v8
	v_cvt_pk_bf16_f32 v10, v6, s0
	s_nop 0
	v_addc_co_u32_e32 v9, vcc, 0, v9, vcc
	global_store_short v[8:9], v10, off

.Lgk_ph9_loop:
	s_waitcnt lgkmcnt(0)
	v_mfma_f32_32x32x16_bf16 v[112:127], v[188:191], v[156:159], v[112:127]
	ds_read_b128 v[200:203], v155
	ds_read_b128 v[172:175], v153
	v_mfma_f32_32x32x16_bf16 v[96:111], v[192:195], v[156:159], v[96:111]
	ds_read_b128 v[204:207], v155 offset:2048
	ds_read_b128 v[176:179], v153 offset:2048
	v_mfma_f32_32x32x16_bf16 v[80:95], v[188:191], v[160:163], v[80:95]
	ds_read_b128 v[180:183], v153 offset:4096
	ds_read_b128 v[184:187], v153 offset:6144
	v_mfma_f32_32x32x16_bf16 v[64:79], v[192:195], v[160:163], v[64:79]
	s_add_u32 m0, s21, 0x22000
	s_nop 0
	global_load_lds_dwordx4 v[216:217], off
	v_lshl_add_u64 v[216:217], v[216:217], 0, s[6:7]
	v_mfma_f32_32x32x16_bf16 v[48:63], v[188:191], v[164:167], v[48:63]
	v_mfma_f32_32x32x16_bf16 v[32:47], v[192:195], v[164:167], v[32:47]
	v_mfma_f32_32x32x16_bf16 v[16:31], v[188:191], v[168:171], v[16:31]
	v_mfma_f32_32x32x16_bf16 v[0:15], v[192:195], v[168:171], v[0:15]
	s_add_u32 m0, s21, 0x26000
	s_nop 0
	global_load_lds_dwordx4 v[220:221], off
	v_lshl_add_u64 v[220:221], v[220:221], 0, s[6:7]
	s_waitcnt lgkmcnt(0)
	s_waitcnt vmcnt(12)
	s_barrier
	s_waitcnt lgkmcnt(0)
	v_mfma_f32_32x32x16_bf16 v[112:127], v[200:203], v[172:175], v[112:127]
	ds_read_b128 v[188:191], v154 offset:32768
	ds_read_b128 v[156:159], v132 offset:32768
	v_mfma_f32_32x32x16_bf16 v[96:111], v[204:207], v[172:175], v[96:111]
	ds_read_b128 v[192:195], v154 offset:34816
	ds_read_b128 v[160:163], v132 offset:34816
	v_mfma_f32_32x32x16_bf16 v[80:95], v[200:203], v[176:179], v[80:95]
	ds_read_b128 v[164:167], v132 offset:36864
	ds_read_b128 v[168:171], v132 offset:38912
	v_mfma_f32_32x32x16_bf16 v[64:79], v[204:207], v[176:179], v[64:79]
	s_add_u32 m0, s21, 0x0
	s_nop 0
	global_load_lds_dwordx4 v[214:215], off
	v_lshl_add_u64 v[214:215], v[214:215], 0, s[6:7]
	v_mfma_f32_32x32x16_bf16 v[48:63], v[200:203], v[180:183], v[48:63]
	v_mfma_f32_32x32x16_bf16 v[32:47], v[204:207], v[180:183], v[32:47]
	v_mfma_f32_32x32x16_bf16 v[16:31], v[200:203], v[184:187], v[16:31]
	v_mfma_f32_32x32x16_bf16 v[0:15], v[204:207], v[184:187], v[0:15]
	s_add_u32 m0, s21, 0x4000
	s_nop 0
	global_load_lds_dwordx4 v[218:219], off
	v_lshl_add_u64 v[218:219], v[218:219], 0, s[6:7]
	s_waitcnt lgkmcnt(0)
	v_mfma_f32_32x32x16_bf16 v[112:127], v[188:191], v[156:159], v[112:127]
	ds_read_b128 v[200:203], v155 offset:32768
	ds_read_b128 v[172:175], v153 offset:32768
	v_mfma_f32_32x32x16_bf16 v[96:111], v[192:195], v[156:159], v[96:111]
	ds_read_b128 v[204:207], v155 offset:34816
	ds_read_b128 v[176:179], v153 offset:34816
	v_mfma_f32_32x32x16_bf16 v[80:95], v[188:191], v[160:163], v[80:95]
	ds_read_b128 v[180:183], v153 offset:36864
	ds_read_b128 v[184:187], v153 offset:38912
	v_mfma_f32_32x32x16_bf16 v[64:79], v[192:195], v[160:163], v[64:79]
	s_add_u32 m0, s21, 0x2000
	s_nop 0
	global_load_lds_dwordx4 v[216:217], off
	v_lshl_add_u64 v[216:217], v[216:217], 0, s[6:7]
	v_mfma_f32_32x32x16_bf16 v[48:63], v[188:191], v[164:167], v[48:63]
	v_mfma_f32_32x32x16_bf16 v[32:47], v[192:195], v[164:167], v[32:47]
	v_mfma_f32_32x32x16_bf16 v[16:31], v[188:191], v[168:171], v[16:31]
	v_mfma_f32_32x32x16_bf16 v[0:15], v[192:195], v[168:171], v[0:15]
	s_add_u32 m0, s21, 0x6000
	s_nop 0
	global_load_lds_dwordx4 v[220:221], off
	v_lshl_add_u64 v[220:221], v[220:221], 0, s[6:7]
	s_waitcnt lgkmcnt(0)
	s_waitcnt vmcnt(12)
	s_barrier
	s_waitcnt lgkmcnt(0)
	v_mfma_f32_32x32x16_bf16 v[112:127], v[200:203], v[172:175], v[112:127]
	ds_read_b128 v[188:191], v208
	ds_read_b128 v[156:159], v198
	v_mfma_f32_32x32x16_bf16 v[96:111], v[204:207], v[172:175], v[96:111]
	ds_read_b128 v[192:195], v208 offset:2048
	ds_read_b128 v[160:163], v198 offset:2048
	v_mfma_f32_32x32x16_bf16 v[80:95], v[200:203], v[176:179], v[80:95]
	ds_read_b128 v[164:167], v198 offset:4096
	ds_read_b128 v[168:171], v198 offset:6144
	v_mfma_f32_32x32x16_bf16 v[64:79], v[204:207], v[176:179], v[64:79]
	s_add_u32 m0, s21, 0x8000
	s_nop 0
	global_load_lds_dwordx4 v[214:215], off
	v_lshl_add_u64 v[214:215], v[214:215], 0, s[6:7]
	v_mfma_f32_32x32x16_bf16 v[48:63], v[200:203], v[180:183], v[48:63]
	v_mfma_f32_32x32x16_bf16 v[32:47], v[204:207], v[180:183], v[32:47]
	v_mfma_f32_32x32x16_bf16 v[16:31], v[200:203], v[184:187], v[16:31]
	v_mfma_f32_32x32x16_bf16 v[0:15], v[204:207], v[184:187], v[0:15]
	s_add_u32 m0, s21, 0xc000
	s_nop 0
	global_load_lds_dwordx4 v[218:219], off
	v_lshl_add_u64 v[218:219], v[218:219], 0, s[6:7]
	s_waitcnt lgkmcnt(0)
	v_mfma_f32_32x32x16_bf16 v[112:127], v[188:191], v[156:159], v[112:127]
	ds_read_b128 v[200:203], v209
	ds_read_b128 v[172:175], v199
	v_mfma_f32_32x32x16_bf16 v[96:111], v[192:195], v[156:159], v[96:111]
	ds_read_b128 v[204:207], v209 offset:2048
	ds_read_b128 v[176:179], v199 offset:2048
	v_mfma_f32_32x32x16_bf16 v[80:95], v[188:191], v[160:163], v[80:95]
	ds_read_b128 v[180:183], v199 offset:4096
	ds_read_b128 v[184:187], v199 offset:6144
	v_mfma_f32_32x32x16_bf16 v[64:79], v[192:195], v[160:163], v[64:79]
	s_add_u32 m0, s21, 0xa000
	s_nop 0
	global_load_lds_dwordx4 v[216:217], off
	v_lshl_add_u64 v[216:217], v[216:217], 0, s[6:7]
	v_mfma_f32_32x32x16_bf16 v[48:63], v[188:191], v[164:167], v[48:63]
	v_mfma_f32_32x32x16_bf16 v[32:47], v[192:195], v[164:167], v[32:47]
	v_mfma_f32_32x32x16_bf16 v[16:31], v[188:191], v[168:171], v[16:31]
	v_mfma_f32_32x32x16_bf16 v[0:15], v[192:195], v[168:171], v[0:15]
	s_add_u32 m0, s21, 0xe000
	s_nop 0
	global_load_lds_dwordx4 v[220:221], off
	v_lshl_add_u64 v[220:221], v[220:221], 0, s[6:7]
	s_waitcnt lgkmcnt(0)
	s_waitcnt vmcnt(12)
	s_barrier
	s_waitcnt lgkmcnt(0)
	v_mfma_f32_32x32x16_bf16 v[112:127], v[200:203], v[172:175], v[112:127]
	ds_read_b128 v[188:191], v208 offset:32768
	ds_read_b128 v[156:159], v198 offset:32768
	v_mfma_f32_32x32x16_bf16 v[96:111], v[204:207], v[172:175], v[96:111]
	ds_read_b128 v[192:195], v208 offset:34816
	ds_read_b128 v[160:163], v198 offset:34816
	v_mfma_f32_32x32x16_bf16 v[80:95], v[200:203], v[176:179], v[80:95]
	ds_read_b128 v[164:167], v198 offset:36864
	ds_read_b128 v[168:171], v198 offset:38912
	v_mfma_f32_32x32x16_bf16 v[64:79], v[204:207], v[176:179], v[64:79]
	s_add_u32 m0, s21, 0x10000
	s_nop 0
	global_load_lds_dwordx4 v[214:215], off
	v_lshl_add_u64 v[214:215], v[214:215], 0, s[6:7]
	v_mfma_f32_32x32x16_bf16 v[48:63], v[200:203], v[180:183], v[48:63]
	v_mfma_f32_32x32x16_bf16 v[32:47], v[204:207], v[180:183], v[32:47]
	v_mfma_f32_32x32x16_bf16 v[16:31], v[200:203], v[184:187], v[16:31]
	v_mfma_f32_32x32x16_bf16 v[0:15], v[204:207], v[184:187], v[0:15]
	s_add_u32 m0, s21, 0x14000
	s_nop 0
	global_load_lds_dwordx4 v[218:219], off
	v_lshl_add_u64 v[218:219], v[218:219], 0, s[6:7]
	s_waitcnt lgkmcnt(0)
	v_mfma_f32_32x32x16_bf16 v[112:127], v[188:191], v[156:159], v[112:127]
	ds_read_b128 v[200:203], v209 offset:32768
	ds_read_b128 v[172:175], v199 offset:32768
	v_mfma_f32_32x32x16_bf16 v[96:111], v[192:195], v[156:159], v[96:111]
	ds_read_b128 v[204:207], v209 offset:34816
	ds_read_b128 v[176:179], v199 offset:34816
	v_mfma_f32_32x32x16_bf16 v[80:95], v[188:191], v[160:163], v[80:95]
	ds_read_b128 v[180:183], v199 offset:36864
	ds_read_b128 v[184:187], v199 offset:38912
	v_mfma_f32_32x32x16_bf16 v[64:79], v[192:195], v[160:163], v[64:79]
	s_add_u32 m0, s21, 0x12000
	s_nop 0
	global_load_lds_dwordx4 v[216:217], off
	v_lshl_add_u64 v[216:217], v[216:217], 0, s[6:7]
	v_mfma_f32_32x32x16_bf16 v[48:63], v[188:191], v[164:167], v[48:63]
	v_mfma_f32_32x32x16_bf16 v[32:47], v[192:195], v[164:167], v[32:47]
	v_mfma_f32_32x32x16_bf16 v[16:31], v[188:191], v[168:171], v[16:31]
	v_mfma_f32_32x32x16_bf16 v[0:15], v[192:195], v[168:171], v[0:15]
	s_add_u32 m0, s21, 0x16000
	s_nop 0
	global_load_lds_dwordx4 v[220:221], off
	v_lshl_add_u64 v[220:221], v[220:221], 0, s[6:7]
	s_waitcnt lgkmcnt(0)
	s_waitcnt vmcnt(12)
	s_barrier
	s_waitcnt lgkmcnt(0)
	v_mfma_f32_32x32x16_bf16 v[112:127], v[200:203], v[172:175], v[112:127]
	ds_read_b128 v[188:191], v212
	ds_read_b128 v[156:159], v210
	v_mfma_f32_32x32x16_bf16 v[96:111], v[204:207], v[172:175], v[96:111]
	ds_read_b128 v[192:195], v212 offset:2048
	ds_read_b128 v[160:163], v210 offset:2048
	v_mfma_f32_32x32x16_bf16 v[80:95], v[200:203], v[176:179], v[80:95]
	ds_read_b128 v[164:167], v210 offset:4096
	ds_read_b128 v[168:171], v210 offset:6144
	v_mfma_f32_32x32x16_bf16 v[64:79], v[204:207], v[176:179], v[64:79]
	s_add_u32 m0, s21, 0x18000
	s_nop 0
	global_load_lds_dwordx4 v[214:215], off
	v_lshl_add_u64 v[214:215], v[214:215], 0, s[6:7]
	v_mfma_f32_32x32x16_bf16 v[48:63], v[200:203], v[180:183], v[48:63]
	v_mfma_f32_32x32x16_bf16 v[32:47], v[204:207], v[180:183], v[32:47]
	v_mfma_f32_32x32x16_bf16 v[16:31], v[200:203], v[184:187], v[16:31]
	v_mfma_f32_32x32x16_bf16 v[0:15], v[204:207], v[184:187], v[0:15]
	s_add_u32 m0, s21, 0x1c000
	s_nop 0
	global_load_lds_dwordx4 v[218:219], off
	v_lshl_add_u64 v[218:219], v[218:219], 0, s[6:7]
	s_waitcnt lgkmcnt(0)
	v_mfma_f32_32x32x16_bf16 v[112:127], v[188:191], v[156:159], v[112:127]
	ds_read_b128 v[200:203], v213
	ds_read_b128 v[172:175], v211
	v_mfma_f32_32x32x16_bf16 v[96:111], v[192:195], v[156:159], v[96:111]
	ds_read_b128 v[204:207], v213 offset:2048
	ds_read_b128 v[176:179], v211 offset:2048
	v_mfma_f32_32x32x16_bf16 v[80:95], v[188:191], v[160:163], v[80:95]
	ds_read_b128 v[180:183], v211 offset:4096
	ds_read_b128 v[184:187], v211 offset:6144
	v_mfma_f32_32x32x16_bf16 v[64:79], v[192:195], v[160:163], v[64:79]
	s_add_u32 m0, s21, 0x1a000
	s_nop 0
	global_load_lds_dwordx4 v[216:217], off
	v_lshl_add_u64 v[216:217], v[216:217], 0, s[6:7]
	v_mfma_f32_32x32x16_bf16 v[48:63], v[188:191], v[164:167], v[48:63]
	v_mfma_f32_32x32x16_bf16 v[32:47], v[192:195], v[164:167], v[32:47]
	v_mfma_f32_32x32x16_bf16 v[16:31], v[188:191], v[168:171], v[16:31]
	v_mfma_f32_32x32x16_bf16 v[0:15], v[192:195], v[168:171], v[0:15]
	s_add_u32 m0, s21, 0x1e000
	s_nop 0
	global_load_lds_dwordx4 v[220:221], off
	v_lshl_add_u64 v[220:221], v[220:221], 0, s[6:7]
	s_waitcnt lgkmcnt(0)
	s_waitcnt vmcnt(12)
	s_barrier
	s_waitcnt lgkmcnt(0)
	v_mfma_f32_32x32x16_bf16 v[112:127], v[200:203], v[172:175], v[112:127]
	ds_read_b128 v[188:191], v154
	ds_read_b128 v[156:159], v132
	v_mfma_f32_32x32x16_bf16 v[96:111], v[204:207], v[172:175], v[96:111]
	ds_read_b128 v[192:195], v154 offset:2048
	ds_read_b128 v[160:163], v132 offset:2048
	v_mfma_f32_32x32x16_bf16 v[80:95], v[200:203], v[176:179], v[80:95]
	ds_read_b128 v[164:167], v132 offset:4096
	ds_read_b128 v[168:171], v132 offset:6144
	v_mfma_f32_32x32x16_bf16 v[64:79], v[204:207], v[176:179], v[64:79]
	s_add_u32 m0, s21, 0x20000
	s_nop 0
	global_load_lds_dwordx4 v[214:215], off
	v_lshl_add_u64 v[214:215], v[214:215], 0, s[6:7]
	v_mfma_f32_32x32x16_bf16 v[48:63], v[200:203], v[180:183], v[48:63]
	v_mfma_f32_32x32x16_bf16 v[32:47], v[204:207], v[180:183], v[32:47]
	v_mfma_f32_32x32x16_bf16 v[16:31], v[200:203], v[184:187], v[16:31]
	v_mfma_f32_32x32x16_bf16 v[0:15], v[204:207], v[184:187], v[0:15]
	s_add_u32 m0, s21, 0x24000
	s_nop 0
	global_load_lds_dwordx4 v[218:219], off
	v_lshl_add_u64 v[218:219], v[218:219], 0, s[6:7]
	s_sub_u32 s25, s25, 1
	s_cmp_lg_u32 s25, 0
	s_cbranch_scc1 .Lgk_ph9_loop
; #define G_LOADA(kt_) { _Pragma("unroll") for (int i = 0; i < 4; ++i) ra[i] = al(lrow + 64 * i, (kt_) * 64 + lck * 8); }
; #define G_LOADB(kt_) { _Pragma("unroll") for (int i = 0; i < 4; ++i) rb[i] = bl(lrow + 64 * i, (kt_) * 64 + lck * 8); }
; #define G_STOREA(buf_) { bf16_t* nA = sA + (buf_) * 256 * GLD; _Pragma("unroll") for (int i = 0; i < 4; ++i) *(u32x4*)(nA + (lrow + 64 * i) * GLD + lck * 8) = ra[i]; }
; #define G_STOREB(buf_) { bf16_t* nB = sB + (buf_) * 256 * GLD; _Pragma("unroll") for (int i = 0; i < 4; ++i) *(u32x4*)(nB + (lrow + 64 * i) * GLD + lck * 8) = rb[i]; }
; template <class AL, class BL, class EP>
; DI void gemm_tile256(AL al, BL bl, EP ep, int K, char* smem) {
;     ...
;   G_LOADA(0); G_LOADB(0);
;   __syncthreads();
;   G_STOREA(0); G_STOREB(0);
;   if (KT > 1) G_LOADB(1);
;   __syncthreads();
;   for (int kt = 0; kt < KT; kt += 2) {
;     G_STEP(0, kt);
;     if (kt + 1 >= KT) break;
;     G_STEP(1, kt + 1);
;   }
	s_waitcnt lgkmcnt(0)
	v_mfma_f32_32x32x16_bf16 v[112:127], v[188:191], v[156:159], v[112:127]
	ds_read_b128 v[200:203], v155
	ds_read_b128 v[172:175], v153
	v_mfma_f32_32x32x16_bf16 v[96:111], v[192:195], v[156:159], v[96:111]
	ds_read_b128 v[204:207], v155 offset:2048
	ds_read_b128 v[176:179], v153 offset:2048
	v_mfma_f32_32x32x16_bf16 v[80:95], v[188:191], v[160:163], v[80:95]
	ds_read_b128 v[180:183], v153 offset:4096
	ds_read_b128 v[184:187], v153 offset:6144
	v_mfma_f32_32x32x16_bf16 v[64:79], v[192:195], v[160:163], v[64:79]
	s_add_u32 m0, s21, 0x22000
	s_nop 0
	global_load_lds_dwordx4 v[216:217], off
	v_lshl_add_u64 v[216:217], v[216:217], 0, s[6:7]
	v_mfma_f32_32x32x16_bf16 v[48:63], v[188:191], v[164:167], v[48:63]
	v_mfma_f32_32x32x16_bf16 v[32:47], v[192:195], v[164:167], v[32:47]
	v_mfma_f32_32x32x16_bf16 v[16:31], v[188:191], v[168:171], v[16:31]
	v_mfma_f32_32x32x16_bf16 v[0:15], v[192:195], v[168:171], v[0:15]
	s_add_u32 m0, s21, 0x26000
	s_nop 0
	global_load_lds_dwordx4 v[220:221], off
	v_lshl_add_u64 v[220:221], v[220:221], 0, s[6:7]
	s_waitcnt lgkmcnt(0)
	s_waitcnt vmcnt(12)
	s_barrier
	s_waitcnt lgkmcnt(0)
	v_mfma_f32_32x32x16_bf16 v[112:127], v[200:203], v[172:175], v[112:127]
	ds_read_b128 v[188:191], v154 offset:32768
	ds_read_b128 v[156:159], v132 offset:32768
	v_mfma_f32_32x32x16_bf16 v[96:111], v[204:207], v[172:175], v[96:111]
	ds_read_b128 v[192:195], v154 offset:34816
	ds_read_b128 v[160:163], v132 offset:34816
	v_mfma_f32_32x32x16_bf16 v[80:95], v[200:203], v[176:179], v[80:95]
	ds_read_b128 v[164:167], v132 offset:36864
	ds_read_b128 v[168:171], v132 offset:38912
	v_mfma_f32_32x32x16_bf16 v[64:79], v[204:207], v[176:179], v[64:79]
	s_add_u32 m0, s21, 0x0
	s_nop 0
	global_load_lds_dwordx4 v[214:215], off
	v_lshl_add_u64 v[214:215], v[214:215], 0, s[6:7]
	v_mfma_f32_32x32x16_bf16 v[48:63], v[200:203], v[180:183], v[48:63]
	v_mfma_f32_32x32x16_bf16 v[32:47], v[204:207], v[180:183], v[32:47]
	v_mfma_f32_32x32x16_bf16 v[16:31], v[200:203], v[184:187], v[16:31]
	v_mfma_f32_32x32x16_bf16 v[0:15], v[204:207], v[184:187], v[0:15]
	s_add_u32 m0, s21, 0x4000
	s_nop 0
	global_load_lds_dwordx4 v[218:219], off
	v_lshl_add_u64 v[218:219], v[218:219], 0, s[6:7]
	s_waitcnt lgkmcnt(0)
	v_mfma_f32_32x32x16_bf16 v[112:127], v[188:191], v[156:159], v[112:127]
	ds_read_b128 v[200:203], v155 offset:32768
	ds_read_b128 v[172:175], v153 offset:32768
	v_mfma_f32_32x32x16_bf16 v[96:111], v[192:195], v[156:159], v[96:111]
	ds_read_b128 v[204:207], v155 offset:34816
	ds_read_b128 v[176:179], v153 offset:34816
	v_mfma_f32_32x32x16_bf16 v[80:95], v[188:191], v[160:163], v[80:95]
	ds_read_b128 v[180:183], v153 offset:36864
	ds_read_b128 v[184:187], v153 offset:38912
	v_mfma_f32_32x32x16_bf16 v[64:79], v[192:195], v[160:163], v[64:79]
	s_add_u32 m0, s21, 0x2000
	s_nop 0
	global_load_lds_dwordx4 v[216:217], off
	v_lshl_add_u64 v[216:217], v[216:217], 0, s[6:7]
	v_mfma_f32_32x32x16_bf16 v[48:63], v[188:191], v[164:167], v[48:63]
	v_mfma_f32_32x32x16_bf16 v[32:47], v[192:195], v[164:167], v[32:47]
	v_mfma_f32_32x32x16_bf16 v[16:31], v[188:191], v[168:171], v[16:31]
	v_mfma_f32_32x32x16_bf16 v[0:15], v[192:195], v[168:171], v[0:15]
	s_add_u32 m0, s21, 0x6000
	s_nop 0
	global_load_lds_dwordx4 v[220:221], off
	v_lshl_add_u64 v[220:221], v[220:221], 0, s[6:7]
	s_waitcnt lgkmcnt(0)
	s_waitcnt vmcnt(12)
	s_barrier
	s_waitcnt lgkmcnt(0)
	v_mfma_f32_32x32x16_bf16 v[112:127], v[200:203], v[172:175], v[112:127]
	ds_read_b128 v[188:191], v208
	ds_read_b128 v[156:159], v198
	v_mfma_f32_32x32x16_bf16 v[96:111], v[204:207], v[172:175], v[96:111]
	ds_read_b128 v[192:195], v208 offset:2048
	ds_read_b128 v[160:163], v198 offset:2048
	v_mfma_f32_32x32x16_bf16 v[80:95], v[200:203], v[176:179], v[80:95]
	ds_read_b128 v[164:167], v198 offset:4096
	ds_read_b128 v[168:171], v198 offset:6144
	v_mfma_f32_32x32x16_bf16 v[64:79], v[204:207], v[176:179], v[64:79]
	s_add_u32 m0, s21, 0x8000
	s_nop 0
	global_load_lds_dwordx4 v[214:215], off
	v_lshl_add_u64 v[214:215], v[214:215], 0, s[6:7]
	v_mfma_f32_32x32x16_bf16 v[48:63], v[200:203], v[180:183], v[48:63]
	v_mfma_f32_32x32x16_bf16 v[32:47], v[204:207], v[180:183], v[32:47]
	v_mfma_f32_32x32x16_bf16 v[16:31], v[200:203], v[184:187], v[16:31]
	v_mfma_f32_32x32x16_bf16 v[0:15], v[204:207], v[184:187], v[0:15]
	s_add_u32 m0, s21, 0xc000
	s_nop 0
	global_load_lds_dwordx4 v[218:219], off
	v_lshl_add_u64 v[218:219], v[218:219], 0, s[6:7]
	s_waitcnt lgkmcnt(0)
	v_mfma_f32_32x32x16_bf16 v[112:127], v[188:191], v[156:159], v[112:127]
	ds_read_b128 v[200:203], v209
	ds_read_b128 v[172:175], v199
	v_mfma_f32_32x32x16_bf16 v[96:111], v[192:195], v[156:159], v[96:111]
	ds_read_b128 v[204:207], v209 offset:2048
	ds_read_b128 v[176:179], v199 offset:2048
	v_mfma_f32_32x32x16_bf16 v[80:95], v[188:191], v[160:163], v[80:95]
	ds_read_b128 v[180:183], v199 offset:4096
	ds_read_b128 v[184:187], v199 offset:6144
	v_mfma_f32_32x32x16_bf16 v[64:79], v[192:195], v[160:163], v[64:79]
	s_add_u32 m0, s21, 0xa000
	s_nop 0
	global_load_lds_dwordx4 v[216:217], off
	v_lshl_add_u64 v[216:217], v[216:217], 0, s[6:7]
	v_mfma_f32_32x32x16_bf16 v[48:63], v[188:191], v[164:167], v[48:63]
	v_mfma_f32_32x32x16_bf16 v[32:47], v[192:195], v[164:167], v[32:47]
	v_mfma_f32_32x32x16_bf16 v[16:31], v[188:191], v[168:171], v[16:31]
	v_mfma_f32_32x32x16_bf16 v[0:15], v[192:195], v[168:171], v[0:15]
	s_add_u32 m0, s21, 0xe000
	s_nop 0
	global_load_lds_dwordx4 v[220:221], off
	v_lshl_add_u64 v[220:221], v[220:221], 0, s[6:7]
	s_waitcnt lgkmcnt(0)
	s_waitcnt vmcnt(12)
	s_barrier
; #define G_LOADA(kt_) { _Pragma("unroll") for (int i = 0; i < 4; ++i) ra[i] = al(lrow + 64 * i, (kt_) * 64 + lck * 8); }
; #define G_LOADB(kt_) { _Pragma("unroll") for (int i = 0; i < 4; ++i) rb[i] = bl(lrow + 64 * i, (kt_) * 64 + lck * 8); }
; #define G_STOREA(buf_) { bf16_t* nA = sA + (buf_) * 256 * GLD; _Pragma("unroll") for (int i = 0; i < 4; ++i) *(u32x4*)(nA + (lrow + 64 * i) * GLD + lck * 8) = ra[i]; }
; #define G_STOREB(buf_) { bf16_t* nB = sB + (buf_) * 256 * GLD; _Pragma("unroll") for (int i = 0; i < 4; ++i) *(u32x4*)(nB + (lrow + 64 * i) * GLD + lck * 8) = rb[i]; }
; template <class AL, class BL, class EP>
; DI void gemm_tile256(AL al, BL bl, EP ep, int K, char* smem) {
;     ...
;   G_LOADA(0); G_LOADB(0);
;   __syncthreads();
;   G_STOREA(0); G_STOREB(0);
;   if (KT > 1) G_LOADB(1);
;   __syncthreads();
;   for (int kt = 0; kt < KT; kt += 2) {
;     G_STEP(0, kt);
;     if (kt + 1 >= KT) break;
;     G_STEP(1, kt + 1);
;   }
	s_waitcnt lgkmcnt(0)
	v_mfma_f32_32x32x16_bf16 v[112:127], v[200:203], v[172:175], v[112:127]
	ds_read_b128 v[188:191], v208 offset:32768
	ds_read_b128 v[156:159], v198 offset:32768
	v_mfma_f32_32x32x16_bf16 v[96:111], v[204:207], v[172:175], v[96:111]
	ds_read_b128 v[192:195], v208 offset:34816
	ds_read_b128 v[160:163], v198 offset:34816
	v_mfma_f32_32x32x16_bf16 v[80:95], v[200:203], v[176:179], v[80:95]
	ds_read_b128 v[164:167], v198 offset:36864
	ds_read_b128 v[168:171], v198 offset:38912
	v_mfma_f32_32x32x16_bf16 v[64:79], v[204:207], v[176:179], v[64:79]
	v_mfma_f32_32x32x16_bf16 v[48:63], v[200:203], v[180:183], v[48:63]
	v_mfma_f32_32x32x16_bf16 v[32:47], v[204:207], v[180:183], v[32:47]
	v_mfma_f32_32x32x16_bf16 v[16:31], v[200:203], v[184:187], v[16:31]
	v_mfma_f32_32x32x16_bf16 v[0:15], v[204:207], v[184:187], v[0:15]
	s_waitcnt lgkmcnt(0)
	v_mfma_f32_32x32x16_bf16 v[112:127], v[188:191], v[156:159], v[112:127]
	ds_read_b128 v[200:203], v209 offset:32768
	ds_read_b128 v[172:175], v199 offset:32768
	v_mfma_f32_32x32x16_bf16 v[96:111], v[192:195], v[156:159], v[96:111]
	ds_read_b128 v[204:207], v209 offset:34816
	ds_read_b128 v[176:179], v199 offset:34816
	v_mfma_f32_32x32x16_bf16 v[80:95], v[188:191], v[160:163], v[80:95]
	ds_read_b128 v[180:183], v199 offset:36864
	ds_read_b128 v[184:187], v199 offset:38912
	v_mfma_f32_32x32x16_bf16 v[64:79], v[192:195], v[160:163], v[64:79]
	v_mfma_f32_32x32x16_bf16 v[48:63], v[188:191], v[164:167], v[48:63]
	v_mfma_f32_32x32x16_bf16 v[32:47], v[192:195], v[164:167], v[32:47]
	v_mfma_f32_32x32x16_bf16 v[16:31], v[188:191], v[168:171], v[16:31]
	v_mfma_f32_32x32x16_bf16 v[0:15], v[192:195], v[168:171], v[0:15]
	s_waitcnt lgkmcnt(0)
	s_waitcnt vmcnt(8)
	s_barrier
	s_waitcnt lgkmcnt(0)
	v_mfma_f32_32x32x16_bf16 v[112:127], v[200:203], v[172:175], v[112:127]
	ds_read_b128 v[188:191], v212
	ds_read_b128 v[156:159], v210
	v_mfma_f32_32x32x16_bf16 v[96:111], v[204:207], v[172:175], v[96:111]
	ds_read_b128 v[192:195], v212 offset:2048
	ds_read_b128 v[160:163], v210 offset:2048
	v_mfma_f32_32x32x16_bf16 v[80:95], v[200:203], v[176:179], v[80:95]
	ds_read_b128 v[164:167], v210 offset:4096
	ds_read_b128 v[168:171], v210 offset:6144
	v_mfma_f32_32x32x16_bf16 v[64:79], v[204:207], v[176:179], v[64:79]
	v_mfma_f32_32x32x16_bf16 v[48:63], v[200:203], v[180:183], v[48:63]
	v_mfma_f32_32x32x16_bf16 v[32:47], v[204:207], v[180:183], v[32:47]
	v_mfma_f32_32x32x16_bf16 v[16:31], v[200:203], v[184:187], v[16:31]
	v_mfma_f32_32x32x16_bf16 v[0:15], v[204:207], v[184:187], v[0:15]
	s_waitcnt lgkmcnt(0)
	v_mfma_f32_32x32x16_bf16 v[112:127], v[188:191], v[156:159], v[112:127]
	ds_read_b128 v[200:203], v213
	ds_read_b128 v[172:175], v211
	v_mfma_f32_32x32x16_bf16 v[96:111], v[192:195], v[156:159], v[96:111]
	ds_read_b128 v[204:207], v213 offset:2048
	ds_read_b128 v[176:179], v211 offset:2048
	v_mfma_f32_32x32x16_bf16 v[80:95], v[188:191], v[160:163], v[80:95]
	ds_read_b128 v[180:183], v211 offset:4096
	ds_read_b128 v[184:187], v211 offset:6144
	v_mfma_f32_32x32x16_bf16 v[64:79], v[192:195], v[160:163], v[64:79]
	v_mfma_f32_32x32x16_bf16 v[48:63], v[188:191], v[164:167], v[48:63]
	v_mfma_f32_32x32x16_bf16 v[32:47], v[192:195], v[164:167], v[32:47]
	v_mfma_f32_32x32x16_bf16 v[16:31], v[188:191], v[168:171], v[16:31]
	v_mfma_f32_32x32x16_bf16 v[0:15], v[192:195], v[168:171], v[0:15]
	s_waitcnt lgkmcnt(0)
	s_waitcnt vmcnt(4)
	s_barrier
	s_waitcnt lgkmcnt(0)
	v_mfma_f32_32x32x16_bf16 v[112:127], v[200:203], v[172:175], v[112:127]
	ds_read_b128 v[188:191], v154
	ds_read_b128 v[156:159], v132
	v_mfma_f32_32x32x16_bf16 v[96:111], v[204:207], v[172:175], v[96:111]
	ds_read_b128 v[192:195], v154 offset:2048
	ds_read_b128 v[160:163], v132 offset:2048
	v_mfma_f32_32x32x16_bf16 v[80:95], v[200:203], v[176:179], v[80:95]
	ds_read_b128 v[164:167], v132 offset:4096
	ds_read_b128 v[168:171], v132 offset:6144
	v_mfma_f32_32x32x16_bf16 v[64:79], v[204:207], v[176:179], v[64:79]
	v_mfma_f32_32x32x16_bf16 v[48:63], v[200:203], v[180:183], v[48:63]
	v_mfma_f32_32x32x16_bf16 v[32:47], v[204:207], v[180:183], v[32:47]
	v_mfma_f32_32x32x16_bf16 v[16:31], v[200:203], v[184:187], v[16:31]
	v_mfma_f32_32x32x16_bf16 v[0:15], v[204:207], v[184:187], v[0:15]
	s_waitcnt lgkmcnt(0)
	v_mfma_f32_32x32x16_bf16 v[112:127], v[188:191], v[156:159], v[112:127]
	ds_read_b128 v[200:203], v155
	ds_read_b128 v[172:175], v153
	v_mfma_f32_32x32x16_bf16 v[96:111], v[192:195], v[156:159], v[96:111]
	ds_read_b128 v[204:207], v155 offset:2048
	ds_read_b128 v[176:179], v153 offset:2048
	v_mfma_f32_32x32x16_bf16 v[80:95], v[188:191], v[160:163], v[80:95]
	ds_read_b128 v[180:183], v153 offset:4096
	ds_read_b128 v[184:187], v153 offset:6144
	v_mfma_f32_32x32x16_bf16 v[64:79], v[192:195], v[160:163], v[64:79]
	v_mfma_f32_32x32x16_bf16 v[48:63], v[188:191], v[164:167], v[48:63]
	v_mfma_f32_32x32x16_bf16 v[32:47], v[192:195], v[164:167], v[32:47]
	v_mfma_f32_32x32x16_bf16 v[16:31], v[188:191], v[168:171], v[16:31]
	v_mfma_f32_32x32x16_bf16 v[0:15], v[192:195], v[168:171], v[0:15]
	s_waitcnt lgkmcnt(0)
	s_waitcnt vmcnt(0)
	s_barrier
; DI unsigned pack2(float a, float b) { f2_t f = {a, b}; bf2_t r = __builtin_convertvector(f, bf2_t); return __builtin_bit_cast(unsigned, r); }
; template <class AL, class BL, class EP>
; DI void gemm_tile256(AL al, BL bl, EP ep, int K, char* smem) {
;     ...
;   if constexpr (EP::kBf16) {
;     bf16_t* sCb = (bf16_t*)smem;
; #pragma unroll
;     for (int i = 0; i < 4; ++i)
; #pragma unroll
;       for (int j = 0; j < 2; ++j)
; #pragma unroll
;         for (int g = 0; g < 4; ++g) {
;           u32x2 v = {pack2(acc[i][j][4 * g], acc[i][j][4 * g + 1]), pack2(acc[i][j][4 * g + 2], acc[i][j][4 * g + 3])};
;           *(u32x2*)(sCb + (128 * wm + 32 * i + r) * BLD + 64 * wn + 32 * j + 8 * g + 4 * h) = v;
;         }
;     __syncthreads();
	s_waitcnt lgkmcnt(0)
	v_mfma_f32_32x32x16_bf16 v[112:127], v[200:203], v[172:175], v[112:127]
	ds_read_b128 v[188:191], v154 offset:32768
	ds_read_b128 v[156:159], v132 offset:32768
	v_mfma_f32_32x32x16_bf16 v[96:111], v[204:207], v[172:175], v[96:111]
	ds_read_b128 v[192:195], v154 offset:34816
	ds_read_b128 v[160:163], v132 offset:34816
	v_mfma_f32_32x32x16_bf16 v[80:95], v[200:203], v[176:179], v[80:95]
	ds_read_b128 v[164:167], v132 offset:36864
	ds_read_b128 v[168:171], v132 offset:38912
	v_mfma_f32_32x32x16_bf16 v[64:79], v[204:207], v[176:179], v[64:79]
	v_mfma_f32_32x32x16_bf16 v[48:63], v[200:203], v[180:183], v[48:63]
	v_mfma_f32_32x32x16_bf16 v[32:47], v[204:207], v[180:183], v[32:47]
	v_mfma_f32_32x32x16_bf16 v[16:31], v[200:203], v[184:187], v[16:31]
	v_mfma_f32_32x32x16_bf16 v[0:15], v[204:207], v[184:187], v[0:15]
	s_waitcnt lgkmcnt(0)
	v_mfma_f32_32x32x16_bf16 v[112:127], v[188:191], v[156:159], v[112:127]
	ds_read_b128 v[200:203], v155 offset:32768
	ds_read_b128 v[172:175], v153 offset:32768
	v_mfma_f32_32x32x16_bf16 v[96:111], v[192:195], v[156:159], v[96:111]
	ds_read_b128 v[204:207], v155 offset:34816
	ds_read_b128 v[176:179], v153 offset:34816
	v_mfma_f32_32x32x16_bf16 v[80:95], v[188:191], v[160:163], v[80:95]
	ds_read_b128 v[180:183], v153 offset:36864
	ds_read_b128 v[184:187], v153 offset:38912
	v_mfma_f32_32x32x16_bf16 v[64:79], v[192:195], v[160:163], v[64:79]
	v_mfma_f32_32x32x16_bf16 v[48:63], v[188:191], v[164:167], v[48:63]
	v_mfma_f32_32x32x16_bf16 v[32:47], v[192:195], v[164:167], v[32:47]
	v_mfma_f32_32x32x16_bf16 v[16:31], v[188:191], v[168:171], v[16:31]
	v_mfma_f32_32x32x16_bf16 v[0:15], v[192:195], v[168:171], v[0:15]
	s_waitcnt lgkmcnt(0)
	s_waitcnt lgkmcnt(0)
	v_mfma_f32_32x32x16_bf16 v[112:127], v[200:203], v[172:175], v[112:127]
	v_mfma_f32_32x32x16_bf16 v[96:111], v[204:207], v[172:175], v[96:111]
	v_mfma_f32_32x32x16_bf16 v[80:95], v[200:203], v[176:179], v[80:95]
	v_mfma_f32_32x32x16_bf16 v[64:79], v[204:207], v[176:179], v[64:79]
	v_mfma_f32_32x32x16_bf16 v[48:63], v[200:203], v[180:183], v[48:63]
	v_mfma_f32_32x32x16_bf16 v[32:47], v[204:207], v[180:183], v[32:47]
	v_mfma_f32_32x32x16_bf16 v[16:31], v[200:203], v[184:187], v[16:31]
	v_mfma_f32_32x32x16_bf16 v[0:15], v[204:207], v[184:187], v[0:15]
	s_nop 15
	s_nop 3
	v_lshl_or_b32 v128, v133, 7, v152
	s_waitcnt lgkmcnt(4)
	v_mad_u64_u32 v[130:131], s[4:5], v151, s46, v[128:129]
	s_and_b32 s24, s52, 0xf00
	s_waitcnt lgkmcnt(0)
	s_barrier
	s_cmp_gt_i32 s20, 3
	s_nop 5
	v_cvt_pk_bf16_f32 v112, v112, v113
	v_cvt_pk_bf16_f32 v113, v114, v115
	v_cvt_pk_bf16_f32 v114, v116, v117
	v_cvt_pk_bf16_f32 v115, v118, v119
	ds_write2_b64 v130, v[112:113], v[114:115] offset1:2
	v_cvt_pk_bf16_f32 v112, v120, v121
	v_cvt_pk_bf16_f32 v113, v122, v123
	v_cvt_pk_bf16_f32 v96, v96, v97
	v_cvt_pk_bf16_f32 v97, v98, v99
	v_cvt_pk_bf16_f32 v98, v100, v101
	v_cvt_pk_bf16_f32 v99, v102, v103
	v_cvt_pk_bf16_f32 v114, v124, v125
	v_cvt_pk_bf16_f32 v115, v126, v127
	ds_write2_b64 v130, v[96:97], v[98:99] offset0:8 offset1:10
	s_nop 3
	v_cvt_pk_bf16_f32 v80, v80, v81
	v_cvt_pk_bf16_f32 v81, v82, v83
	v_cvt_pk_bf16_f32 v82, v84, v85
	v_cvt_pk_bf16_f32 v83, v86, v87
	v_add_u32_e32 v84, 0x4000, v130
	v_cvt_pk_bf16_f32 v96, v104, v105
	v_cvt_pk_bf16_f32 v97, v106, v107
	v_cvt_pk_bf16_f32 v64, v64, v65
	v_cvt_pk_bf16_f32 v65, v66, v67
	v_cvt_pk_bf16_f32 v66, v68, v69
	v_cvt_pk_bf16_f32 v67, v70, v71
	v_cvt_pk_bf16_f32 v98, v108, v109
	v_cvt_pk_bf16_f32 v99, v110, v111
	ds_write2_b64 v84, v[80:81], v[82:83] offset0:64 offset1:66
	s_nop 3
	v_cvt_pk_bf16_f32 v48, v48, v49
	v_cvt_pk_bf16_f32 v49, v50, v51
	v_cvt_pk_bf16_f32 v50, v52, v53
	v_cvt_pk_bf16_f32 v51, v54, v55
	v_add_u32_e32 v52, 0x8000, v130
	v_cvt_pk_bf16_f32 v80, v88, v89
	v_cvt_pk_bf16_f32 v81, v90, v91
	v_cvt_pk_bf16_f32 v32, v32, v33
	v_cvt_pk_bf16_f32 v33, v34, v35
	v_cvt_pk_bf16_f32 v34, v36, v37
	v_cvt_pk_bf16_f32 v35, v38, v39
	v_cvt_pk_bf16_f32 v82, v92, v93
	v_cvt_pk_bf16_f32 v83, v94, v95
	ds_write2_b64 v84, v[64:65], v[66:67] offset0:72 offset1:74
	s_nop 3
	v_cvt_pk_bf16_f32 v16, v16, v17
	v_cvt_pk_bf16_f32 v17, v18, v19
	v_cvt_pk_bf16_f32 v18, v20, v21
	v_cvt_pk_bf16_f32 v19, v22, v23
	v_add_u32_e32 v20, 0xc000, v130
	v_cvt_pk_bf16_f32 v64, v72, v73
	v_cvt_pk_bf16_f32 v65, v74, v75
	s_nop 0
	v_cvt_pk_bf16_f32 v0, v0, v1
	v_cvt_pk_bf16_f32 v1, v2, v3
	v_cvt_pk_bf16_f32 v2, v4, v5
	v_cvt_pk_bf16_f32 v3, v6, v7
	v_cvt_pk_bf16_f32 v66, v76, v77
	v_cvt_pk_bf16_f32 v67, v78, v79
	ds_write2_b64 v52, v[48:49], v[50:51] offset0:128 offset1:130
	v_cvt_pk_bf16_f32 v48, v56, v57
	v_cvt_pk_bf16_f32 v49, v58, v59
	v_cvt_pk_bf16_f32 v50, v60, v61
	v_cvt_pk_bf16_f32 v51, v62, v63
	ds_write2_b64 v52, v[32:33], v[34:35] offset0:136 offset1:138
	v_cvt_pk_bf16_f32 v32, v40, v41
	v_cvt_pk_bf16_f32 v33, v42, v43
	v_cvt_pk_bf16_f32 v34, v44, v45
	v_cvt_pk_bf16_f32 v35, v46, v47
	ds_write2_b64 v20, v[16:17], v[18:19] offset0:192 offset1:194
	v_cvt_pk_bf16_f32 v16, v24, v25
	v_cvt_pk_bf16_f32 v17, v26, v27
	v_cvt_pk_bf16_f32 v18, v28, v29
	v_cvt_pk_bf16_f32 v19, v30, v31
	ds_write2_b64 v20, v[0:1], v[2:3] offset0:200 offset1:202
	v_cvt_pk_bf16_f32 v0, v8, v9
	v_cvt_pk_bf16_f32 v1, v10, v11
	v_cvt_pk_bf16_f32 v2, v12, v13
	v_cvt_pk_bf16_f32 v3, v14, v15
	ds_write2_b64 v130, v[112:113], v[114:115] offset0:4 offset1:6
	ds_write2_b64 v130, v[96:97], v[98:99] offset0:12 offset1:14
	ds_write2_b64 v84, v[80:81], v[82:83] offset0:68 offset1:70
	ds_write2_b64 v84, v[64:65], v[66:67] offset0:76 offset1:78
	ds_write2_b64 v52, v[48:49], v[50:51] offset0:132 offset1:134
	ds_write2_b64 v52, v[32:33], v[34:35] offset0:140 offset1:142
	ds_write2_b64 v20, v[16:17], v[18:19] offset0:196 offset1:198
	ds_write2_b64 v20, v[0:1], v[2:3] offset0:204 offset1:206
	s_waitcnt lgkmcnt(0)
	s_barrier
; DI float bf2f(bf16_t v) { return __uint_as_float(((unsigned)v) << 16); }
; DI bf16_t f2bf(float x) { return (bf16_t)(pack2(x, 0.f) & 0xffffu); }
; DI int tid512() { int t = threadIdx_x_raw(); asm volatile("" : "+v"(t)); return t; }
;   DI void operator()(bf16_t* sCb) const {
;     ...
;     if (nt2 < 4) {
;       const float2* rope = (const float2*)(ws + OFF_ROPER);
;       const float sc = (nt2 >= 2) ? 0.08838834764831845f : 1.f;
;       for (int id = tid512(); id < 256 * 128; id += 512) {
;         int row = id >> 7, hf = (id >> 6) & 1, i = id & 63;
;         float2 cs = rope[(size_t)(s0 + row) * 64 + i];
;         bf16_t* q1 = sCb + row * BLD + 128 * hf + i;
;         float x1 = bf2f(q1[0]), x2 = bf2f(q1[64]);
;         q1[0] = f2bf((x1 * cs.x - x2 * cs.y) * sc);
;         q1[64] = f2bf((x1 * cs.y + x2 * cs.x) * sc);
;       }
;       __syncthreads();
	s_cbranch_scc1 .LBB0_771
	v_mov_b32_e32 v2, v196
	s_nop 0
	v_cmp_gt_i32_e32 vcc, s47, v2
	s_and_saveexec_b64 s[4:5], vcc
	s_cbranch_execz .LBB0_770
	s_cmp_gt_i32 s20, 1
	v_and_b32_e32 v4, 63, v196
	s_cselect_b64 vcc, -1, 0
	v_lshrrev_b32_e32 v8, 7, v196
	v_cndmask_b32_e32 v3, 1.0, v150, vcc
	v_mul_lo_u32 v12, v8, s46
	v_lshlrev_b32_e32 v13, 1, v196
	v_and_b32_e32 v13, 0x80, v13
	v_lshlrev_b32_e32 v13, 1, v13
	v_lshlrev_b32_e32 v14, 1, v4
	v_add3_u32 v12, v12, v13, v14
	v_add_u32_e32 v15, s24, v8
	v_lshlrev_b32_e32 v15, 9, v15
	v_lshl_add_u32 v16, v4, 3, v15
	v_add_u32_e32 v17, 0x1000, v16
	v_add_u32_e32 v18, 0x2000, v16
	v_add_u32_e32 v19, 0x3000, v16
	v_add_u32_e32 v20, 0x4000, v16
	v_add_u32_e32 v21, 0x5000, v16
	v_add_u32_e32 v22, 0x6000, v16
	v_add_u32_e32 v23, 0x7000, v16
	s_lshl_b32 s10, s46, 2
	global_load_dwordx2 v[200:201], v16, s[2:3]
	global_load_dwordx2 v[202:203], v16, s[2:3] offset:2048
	global_load_dwordx2 v[204:205], v17, s[2:3]
	global_load_dwordx2 v[206:207], v17, s[2:3] offset:2048
	global_load_dwordx2 v[208:209], v18, s[2:3]
	global_load_dwordx2 v[210:211], v18, s[2:3] offset:2048
	global_load_dwordx2 v[212:213], v19, s[2:3]
	global_load_dwordx2 v[214:215], v19, s[2:3] offset:2048
	global_load_dwordx2 v[216:217], v20, s[2:3]
	global_load_dwordx2 v[218:219], v20, s[2:3] offset:2048
	global_load_dwordx2 v[220:221], v21, s[2:3]
	global_load_dwordx2 v[222:223], v21, s[2:3] offset:2048
	global_load_dwordx2 v[224:225], v22, s[2:3]
	global_load_dwordx2 v[226:227], v22, s[2:3] offset:2048
	global_load_dwordx2 v[228:229], v23, s[2:3]
	global_load_dwordx2 v[230:231], v23, s[2:3] offset:2048
	ds_read_u16 v9, v12
	ds_read_u16 v10, v12 offset:128
	s_waitcnt vmcnt(15)
	s_waitcnt lgkmcnt(1)
	v_lshlrev_b32_e32 v9, 16, v9
	s_waitcnt lgkmcnt(0)
	v_lshlrev_b32_e32 v10, 16, v10
	v_mul_f32_e32 v11, v201, v10
	v_mul_f32_e32 v10, v200, v10
	v_fma_f32 v6, v200, v9, -v11
	v_fmac_f32_e32 v10, v201, v9
	v_mul_f32_e32 v6, v3, v6
	v_mul_f32_e32 v7, v3, v10
	v_cvt_pk_bf16_f32 v6, v6, s0
	v_cvt_pk_bf16_f32 v7, v7, s0
	ds_write_b16 v12, v6
	ds_write_b16 v12, v7 offset:128
	v_add_u32_e32 v16, 0x8000, v16
	global_load_dwordx2 v[200:201], v16, s[2:3]
	v_add_u32_e32 v12, s10, v12
	ds_read_u16 v9, v12
	ds_read_u16 v10, v12 offset:128
	s_waitcnt vmcnt(15)
	s_waitcnt lgkmcnt(1)
	v_lshlrev_b32_e32 v9, 16, v9
	s_waitcnt lgkmcnt(0)
	v_lshlrev_b32_e32 v10, 16, v10
	v_mul_f32_e32 v11, v203, v10
	v_mul_f32_e32 v10, v202, v10
	v_fma_f32 v6, v202, v9, -v11
	v_fmac_f32_e32 v10, v203, v9
	v_mul_f32_e32 v6, v3, v6
	v_mul_f32_e32 v7, v3, v10
	v_cvt_pk_bf16_f32 v6, v6, s0
	v_cvt_pk_bf16_f32 v7, v7, s0
	ds_write_b16 v12, v6
	ds_write_b16 v12, v7 offset:128
	global_load_dwordx2 v[202:203], v16, s[2:3] offset:2048
	v_add_u32_e32 v12, s10, v12
	ds_read_u16 v9, v12
	ds_read_u16 v10, v12 offset:128
	s_waitcnt vmcnt(15)
	s_waitcnt lgkmcnt(1)
	v_lshlrev_b32_e32 v9, 16, v9
	s_waitcnt lgkmcnt(0)
	v_lshlrev_b32_e32 v10, 16, v10
	v_mul_f32_e32 v11, v205, v10
	v_mul_f32_e32 v10, v204, v10
	v_fma_f32 v6, v204, v9, -v11
	v_fmac_f32_e32 v10, v205, v9
	v_mul_f32_e32 v6, v3, v6
	v_mul_f32_e32 v7, v3, v10
	v_cvt_pk_bf16_f32 v6, v6, s0
	v_cvt_pk_bf16_f32 v7, v7, s0
	ds_write_b16 v12, v6
	ds_write_b16 v12, v7 offset:128
	v_add_u32_e32 v17, 0x8000, v17
	global_load_dwordx2 v[204:205], v17, s[2:3]
	v_add_u32_e32 v12, s10, v12
	ds_read_u16 v9, v12
	ds_read_u16 v10, v12 offset:128
	s_waitcnt vmcnt(15)
	s_waitcnt lgkmcnt(1)
	v_lshlrev_b32_e32 v9, 16, v9
	s_waitcnt lgkmcnt(0)
	v_lshlrev_b32_e32 v10, 16, v10
	v_mul_f32_e32 v11, v207, v10
	v_mul_f32_e32 v10, v206, v10
	v_fma_f32 v6, v206, v9, -v11
	v_fmac_f32_e32 v10, v207, v9
	v_mul_f32_e32 v6, v3, v6
	v_mul_f32_e32 v7, v3, v10
	v_cvt_pk_bf16_f32 v6, v6, s0
	v_cvt_pk_bf16_f32 v7, v7, s0
	ds_write_b16 v12, v6
	ds_write_b16 v12, v7 offset:128
	global_load_dwordx2 v[206:207], v17, s[2:3] offset:2048
	v_add_u32_e32 v12, s10, v12
	ds_read_u16 v9, v12
	ds_read_u16 v10, v12 offset:128
	s_waitcnt vmcnt(15)
	s_waitcnt lgkmcnt(1)
	v_lshlrev_b32_e32 v9, 16, v9
	s_waitcnt lgkmcnt(0)
	v_lshlrev_b32_e32 v10, 16, v10
	v_mul_f32_e32 v11, v209, v10
	v_mul_f32_e32 v10, v208, v10
	v_fma_f32 v6, v208, v9, -v11
	v_fmac_f32_e32 v10, v209, v9
	v_mul_f32_e32 v6, v3, v6
	v_mul_f32_e32 v7, v3, v10
	v_cvt_pk_bf16_f32 v6, v6, s0
	v_cvt_pk_bf16_f32 v7, v7, s0
	ds_write_b16 v12, v6
	ds_write_b16 v12, v7 offset:128
	v_add_u32_e32 v18, 0x8000, v18
	global_load_dwordx2 v[208:209], v18, s[2:3]
	v_add_u32_e32 v12, s10, v12
	ds_read_u16 v9, v12
	ds_read_u16 v10, v12 offset:128
	s_waitcnt vmcnt(15)
	s_waitcnt lgkmcnt(1)
	v_lshlrev_b32_e32 v9, 16, v9
	s_waitcnt lgkmcnt(0)
	v_lshlrev_b32_e32 v10, 16, v10
	v_mul_f32_e32 v11, v211, v10
	v_mul_f32_e32 v10, v210, v10
	v_fma_f32 v6, v210, v9, -v11
	v_fmac_f32_e32 v10, v211, v9
	v_mul_f32_e32 v6, v3, v6
	v_mul_f32_e32 v7, v3, v10
	v_cvt_pk_bf16_f32 v6, v6, s0
	v_cvt_pk_bf16_f32 v7, v7, s0
	ds_write_b16 v12, v6
	ds_write_b16 v12, v7 offset:128
	global_load_dwordx2 v[210:211], v18, s[2:3] offset:2048
	v_add_u32_e32 v12, s10, v12
	ds_read_u16 v9, v12
	ds_read_u16 v10, v12 offset:128
	s_waitcnt vmcnt(15)
	s_waitcnt lgkmcnt(1)
	v_lshlrev_b32_e32 v9, 16, v9
	s_waitcnt lgkmcnt(0)
	v_lshlrev_b32_e32 v10, 16, v10
	v_mul_f32_e32 v11, v213, v10
	v_mul_f32_e32 v10, v212, v10
	v_fma_f32 v6, v212, v9, -v11
	v_fmac_f32_e32 v10, v213, v9
	v_mul_f32_e32 v6, v3, v6
	v_mul_f32_e32 v7, v3, v10
	v_cvt_pk_bf16_f32 v6, v6, s0
	v_cvt_pk_bf16_f32 v7, v7, s0
	ds_write_b16 v12, v6
	ds_write_b16 v12, v7 offset:128
	v_add_u32_e32 v19, 0x8000, v19
	global_load_dwordx2 v[212:213], v19, s[2:3]
	v_add_u32_e32 v12, s10, v12
	ds_read_u16 v9, v12
	ds_read_u16 v10, v12 offset:128
	s_waitcnt vmcnt(15)
; DI float bf2f(bf16_t v) { return __uint_as_float(((unsigned)v) << 16); }
; DI bf16_t f2bf(float x) { return (bf16_t)(pack2(x, 0.f) & 0xffffu); }
; DI int tid512() { int t = threadIdx_x_raw(); asm volatile("" : "+v"(t)); return t; }
;   DI void operator()(bf16_t* sCb) const {
;     ...
;     if (nt2 < 4) {
;       const float2* rope = (const float2*)(ws + OFF_ROPER);
;       const float sc = (nt2 >= 2) ? 0.08838834764831845f : 1.f;
;       for (int id = tid512(); id < 256 * 128; id += 512) {
;         int row = id >> 7, hf = (id >> 6) & 1, i = id & 63;
;         float2 cs = rope[(size_t)(s0 + row) * 64 + i];
;         bf16_t* q1 = sCb + row * BLD + 128 * hf + i;
;         float x1 = bf2f(q1[0]), x2 = bf2f(q1[64]);
;         q1[0] = f2bf((x1 * cs.x - x2 * cs.y) * sc);
;         q1[64] = f2bf((x1 * cs.y + x2 * cs.x) * sc);
;       }
;       __syncthreads();
	s_waitcnt lgkmcnt(1)
	v_lshlrev_b32_e32 v9, 16, v9
	s_waitcnt lgkmcnt(0)
	v_lshlrev_b32_e32 v10, 16, v10
	v_mul_f32_e32 v11, v215, v10
	v_mul_f32_e32 v10, v214, v10
	v_fma_f32 v6, v214, v9, -v11
	v_fmac_f32_e32 v10, v215, v9
	v_mul_f32_e32 v6, v3, v6
	v_mul_f32_e32 v7, v3, v10
	v_cvt_pk_bf16_f32 v6, v6, s0
	v_cvt_pk_bf16_f32 v7, v7, s0
	ds_write_b16 v12, v6
	ds_write_b16 v12, v7 offset:128
	global_load_dwordx2 v[214:215], v19, s[2:3] offset:2048
	v_add_u32_e32 v12, s10, v12
	ds_read_u16 v9, v12
	ds_read_u16 v10, v12 offset:128
	s_waitcnt vmcnt(15)
	s_waitcnt lgkmcnt(1)
	v_lshlrev_b32_e32 v9, 16, v9
	s_waitcnt lgkmcnt(0)
	v_lshlrev_b32_e32 v10, 16, v10
	v_mul_f32_e32 v11, v217, v10
	v_mul_f32_e32 v10, v216, v10
	v_fma_f32 v6, v216, v9, -v11
	v_fmac_f32_e32 v10, v217, v9
	v_mul_f32_e32 v6, v3, v6
	v_mul_f32_e32 v7, v3, v10
	v_cvt_pk_bf16_f32 v6, v6, s0
	v_cvt_pk_bf16_f32 v7, v7, s0
	ds_write_b16 v12, v6
	ds_write_b16 v12, v7 offset:128
	v_add_u32_e32 v20, 0x8000, v20
	global_load_dwordx2 v[216:217], v20, s[2:3]
	v_add_u32_e32 v12, s10, v12
	ds_read_u16 v9, v12
	ds_read_u16 v10, v12 offset:128
	s_waitcnt vmcnt(15)
	s_waitcnt lgkmcnt(1)
	v_lshlrev_b32_e32 v9, 16, v9
	s_waitcnt lgkmcnt(0)
	v_lshlrev_b32_e32 v10, 16, v10
	v_mul_f32_e32 v11, v219, v10
	v_mul_f32_e32 v10, v218, v10
	v_fma_f32 v6, v218, v9, -v11
	v_fmac_f32_e32 v10, v219, v9
	v_mul_f32_e32 v6, v3, v6
	v_mul_f32_e32 v7, v3, v10
	v_cvt_pk_bf16_f32 v6, v6, s0
	v_cvt_pk_bf16_f32 v7, v7, s0
	ds_write_b16 v12, v6
	ds_write_b16 v12, v7 offset:128
	global_load_dwordx2 v[218:219], v20, s[2:3] offset:2048
	v_add_u32_e32 v12, s10, v12
	ds_read_u16 v9, v12
	ds_read_u16 v10, v12 offset:128
	s_waitcnt vmcnt(15)
	s_waitcnt lgkmcnt(1)
	v_lshlrev_b32_e32 v9, 16, v9
	s_waitcnt lgkmcnt(0)
	v_lshlrev_b32_e32 v10, 16, v10
	v_mul_f32_e32 v11, v221, v10
	v_mul_f32_e32 v10, v220, v10
	v_fma_f32 v6, v220, v9, -v11
	v_fmac_f32_e32 v10, v221, v9
	v_mul_f32_e32 v6, v3, v6
	v_mul_f32_e32 v7, v3, v10
	v_cvt_pk_bf16_f32 v6, v6, s0
	v_cvt_pk_bf16_f32 v7, v7, s0
	ds_write_b16 v12, v6
	ds_write_b16 v12, v7 offset:128
	v_add_u32_e32 v21, 0x8000, v21
	global_load_dwordx2 v[220:221], v21, s[2:3]
	v_add_u32_e32 v12, s10, v12
	ds_read_u16 v9, v12
	ds_read_u16 v10, v12 offset:128
	s_waitcnt vmcnt(15)
	s_waitcnt lgkmcnt(1)
	v_lshlrev_b32_e32 v9, 16, v9
	s_waitcnt lgkmcnt(0)
	v_lshlrev_b32_e32 v10, 16, v10
	v_mul_f32_e32 v11, v223, v10
	v_mul_f32_e32 v10, v222, v10
	v_fma_f32 v6, v222, v9, -v11
	v_fmac_f32_e32 v10, v223, v9
	v_mul_f32_e32 v6, v3, v6
	v_mul_f32_e32 v7, v3, v10
	v_cvt_pk_bf16_f32 v6, v6, s0
	v_cvt_pk_bf16_f32 v7, v7, s0
	ds_write_b16 v12, v6
	ds_write_b16 v12, v7 offset:128
	global_load_dwordx2 v[222:223], v21, s[2:3] offset:2048
	v_add_u32_e32 v12, s10, v12
	ds_read_u16 v9, v12
	ds_read_u16 v10, v12 offset:128
	s_waitcnt vmcnt(15)
	s_waitcnt lgkmcnt(1)
	v_lshlrev_b32_e32 v9, 16, v9
	s_waitcnt lgkmcnt(0)
	v_lshlrev_b32_e32 v10, 16, v10
	v_mul_f32_e32 v11, v225, v10
	v_mul_f32_e32 v10, v224, v10
	v_fma_f32 v6, v224, v9, -v11
	v_fmac_f32_e32 v10, v225, v9
	v_mul_f32_e32 v6, v3, v6
	v_mul_f32_e32 v7, v3, v10
	v_cvt_pk_bf16_f32 v6, v6, s0
	v_cvt_pk_bf16_f32 v7, v7, s0
	ds_write_b16 v12, v6
	ds_write_b16 v12, v7 offset:128
	v_add_u32_e32 v22, 0x8000, v22
	global_load_dwordx2 v[224:225], v22, s[2:3]
	v_add_u32_e32 v12, s10, v12
	ds_read_u16 v9, v12
	ds_read_u16 v10, v12 offset:128
	s_waitcnt vmcnt(15)
	s_waitcnt lgkmcnt(1)
	v_lshlrev_b32_e32 v9, 16, v9
	s_waitcnt lgkmcnt(0)
	v_lshlrev_b32_e32 v10, 16, v10
	v_mul_f32_e32 v11, v227, v10
	v_mul_f32_e32 v10, v226, v10
	v_fma_f32 v6, v226, v9, -v11
	v_fmac_f32_e32 v10, v227, v9
	v_mul_f32_e32 v6, v3, v6
	v_mul_f32_e32 v7, v3, v10
	v_cvt_pk_bf16_f32 v6, v6, s0
	v_cvt_pk_bf16_f32 v7, v7, s0
	ds_write_b16 v12, v6
	ds_write_b16 v12, v7 offset:128
	global_load_dwordx2 v[226:227], v22, s[2:3] offset:2048
	v_add_u32_e32 v12, s10, v12
	ds_read_u16 v9, v12
	ds_read_u16 v10, v12 offset:128
	s_waitcnt vmcnt(15)
	s_waitcnt lgkmcnt(1)
	v_lshlrev_b32_e32 v9, 16, v9
	s_waitcnt lgkmcnt(0)
	v_lshlrev_b32_e32 v10, 16, v10
	v_mul_f32_e32 v11, v229, v10
	v_mul_f32_e32 v10, v228, v10
	v_fma_f32 v6, v228, v9, -v11
	v_fmac_f32_e32 v10, v229, v9
	v_mul_f32_e32 v6, v3, v6
	v_mul_f32_e32 v7, v3, v10
	v_cvt_pk_bf16_f32 v6, v6, s0
	v_cvt_pk_bf16_f32 v7, v7, s0
	ds_write_b16 v12, v6
	ds_write_b16 v12, v7 offset:128
	v_add_u32_e32 v23, 0x8000, v23
	global_load_dwordx2 v[228:229], v23, s[2:3]
	v_add_u32_e32 v12, s10, v12
	ds_read_u16 v9, v12
	ds_read_u16 v10, v12 offset:128
	s_waitcnt vmcnt(15)
	s_waitcnt lgkmcnt(1)
	v_lshlrev_b32_e32 v9, 16, v9
	s_waitcnt lgkmcnt(0)
	v_lshlrev_b32_e32 v10, 16, v10
	v_mul_f32_e32 v11, v231, v10
	v_mul_f32_e32 v10, v230, v10
	v_fma_f32 v6, v230, v9, -v11
	v_fmac_f32_e32 v10, v231, v9
	v_mul_f32_e32 v6, v3, v6
	v_mul_f32_e32 v7, v3, v10
	v_cvt_pk_bf16_f32 v6, v6, s0
	v_cvt_pk_bf16_f32 v7, v7, s0
	ds_write_b16 v12, v6
	ds_write_b16 v12, v7 offset:128
	global_load_dwordx2 v[230:231], v23, s[2:3] offset:2048
	v_add_u32_e32 v12, s10, v12
	ds_read_u16 v9, v12
	ds_read_u16 v10, v12 offset:128
	s_waitcnt vmcnt(15)
	s_waitcnt lgkmcnt(1)
	v_lshlrev_b32_e32 v9, 16, v9
	s_waitcnt lgkmcnt(0)
	v_lshlrev_b32_e32 v10, 16, v10
	v_mul_f32_e32 v11, v201, v10
	v_mul_f32_e32 v10, v200, v10
	v_fma_f32 v6, v200, v9, -v11
	v_fmac_f32_e32 v10, v201, v9
	v_mul_f32_e32 v6, v3, v6
	v_mul_f32_e32 v7, v3, v10
	v_cvt_pk_bf16_f32 v6, v6, s0
	v_cvt_pk_bf16_f32 v7, v7, s0
	ds_write_b16 v12, v6
	ds_write_b16 v12, v7 offset:128
	v_add_u32_e32 v16, 0x8000, v16
	global_load_dwordx2 v[200:201], v16, s[2:3]
	v_add_u32_e32 v12, s10, v12
	ds_read_u16 v9, v12
	ds_read_u16 v10, v12 offset:128
	s_waitcnt vmcnt(15)
; DI float bf2f(bf16_t v) { return __uint_as_float(((unsigned)v) << 16); }
; DI bf16_t f2bf(float x) { return (bf16_t)(pack2(x, 0.f) & 0xffffu); }
; DI int tid512() { int t = threadIdx_x_raw(); asm volatile("" : "+v"(t)); return t; }
;   DI void operator()(bf16_t* sCb) const {
;     ...
;     if (nt2 < 4) {
;       const float2* rope = (const float2*)(ws + OFF_ROPER);
;       const float sc = (nt2 >= 2) ? 0.08838834764831845f : 1.f;
;       for (int id = tid512(); id < 256 * 128; id += 512) {
;         int row = id >> 7, hf = (id >> 6) & 1, i = id & 63;
;         float2 cs = rope[(size_t)(s0 + row) * 64 + i];
;         bf16_t* q1 = sCb + row * BLD + 128 * hf + i;
;         float x1 = bf2f(q1[0]), x2 = bf2f(q1[64]);
;         q1[0] = f2bf((x1 * cs.x - x2 * cs.y) * sc);
;         q1[64] = f2bf((x1 * cs.y + x2 * cs.x) * sc);
;       }
;       __syncthreads();
	s_waitcnt lgkmcnt(1)
	v_lshlrev_b32_e32 v9, 16, v9
	s_waitcnt lgkmcnt(0)
	v_lshlrev_b32_e32 v10, 16, v10
	v_mul_f32_e32 v11, v203, v10
	v_mul_f32_e32 v10, v202, v10
	v_fma_f32 v6, v202, v9, -v11
	v_fmac_f32_e32 v10, v203, v9
	v_mul_f32_e32 v6, v3, v6
	v_mul_f32_e32 v7, v3, v10
	v_cvt_pk_bf16_f32 v6, v6, s0
	v_cvt_pk_bf16_f32 v7, v7, s0
	ds_write_b16 v12, v6
	ds_write_b16 v12, v7 offset:128
	global_load_dwordx2 v[202:203], v16, s[2:3] offset:2048
	v_add_u32_e32 v12, s10, v12
	ds_read_u16 v9, v12
	ds_read_u16 v10, v12 offset:128
	s_waitcnt vmcnt(15)
	s_waitcnt lgkmcnt(1)
	v_lshlrev_b32_e32 v9, 16, v9
	s_waitcnt lgkmcnt(0)
	v_lshlrev_b32_e32 v10, 16, v10
	v_mul_f32_e32 v11, v205, v10
	v_mul_f32_e32 v10, v204, v10
	v_fma_f32 v6, v204, v9, -v11
	v_fmac_f32_e32 v10, v205, v9
	v_mul_f32_e32 v6, v3, v6
	v_mul_f32_e32 v7, v3, v10
	v_cvt_pk_bf16_f32 v6, v6, s0
	v_cvt_pk_bf16_f32 v7, v7, s0
	ds_write_b16 v12, v6
	ds_write_b16 v12, v7 offset:128
	v_add_u32_e32 v17, 0x8000, v17
	global_load_dwordx2 v[204:205], v17, s[2:3]
	v_add_u32_e32 v12, s10, v12
	ds_read_u16 v9, v12
	ds_read_u16 v10, v12 offset:128
	s_waitcnt vmcnt(15)
	s_waitcnt lgkmcnt(1)
	v_lshlrev_b32_e32 v9, 16, v9
	s_waitcnt lgkmcnt(0)
	v_lshlrev_b32_e32 v10, 16, v10
	v_mul_f32_e32 v11, v207, v10
	v_mul_f32_e32 v10, v206, v10
	v_fma_f32 v6, v206, v9, -v11
	v_fmac_f32_e32 v10, v207, v9
	v_mul_f32_e32 v6, v3, v6
	v_mul_f32_e32 v7, v3, v10
	v_cvt_pk_bf16_f32 v6, v6, s0
	v_cvt_pk_bf16_f32 v7, v7, s0
	ds_write_b16 v12, v6
	ds_write_b16 v12, v7 offset:128
	global_load_dwordx2 v[206:207], v17, s[2:3] offset:2048
	v_add_u32_e32 v12, s10, v12
	ds_read_u16 v9, v12
	ds_read_u16 v10, v12 offset:128
	s_waitcnt vmcnt(15)
	s_waitcnt lgkmcnt(1)
	v_lshlrev_b32_e32 v9, 16, v9
	s_waitcnt lgkmcnt(0)
	v_lshlrev_b32_e32 v10, 16, v10
	v_mul_f32_e32 v11, v209, v10
	v_mul_f32_e32 v10, v208, v10
	v_fma_f32 v6, v208, v9, -v11
	v_fmac_f32_e32 v10, v209, v9
	v_mul_f32_e32 v6, v3, v6
	v_mul_f32_e32 v7, v3, v10
	v_cvt_pk_bf16_f32 v6, v6, s0
	v_cvt_pk_bf16_f32 v7, v7, s0
	ds_write_b16 v12, v6
	ds_write_b16 v12, v7 offset:128
	v_add_u32_e32 v18, 0x8000, v18
	global_load_dwordx2 v[208:209], v18, s[2:3]
	v_add_u32_e32 v12, s10, v12
	ds_read_u16 v9, v12
	ds_read_u16 v10, v12 offset:128
	s_waitcnt vmcnt(15)
	s_waitcnt lgkmcnt(1)
	v_lshlrev_b32_e32 v9, 16, v9
	s_waitcnt lgkmcnt(0)
	v_lshlrev_b32_e32 v10, 16, v10
	v_mul_f32_e32 v11, v211, v10
	v_mul_f32_e32 v10, v210, v10
	v_fma_f32 v6, v210, v9, -v11
	v_fmac_f32_e32 v10, v211, v9
	v_mul_f32_e32 v6, v3, v6
	v_mul_f32_e32 v7, v3, v10
	v_cvt_pk_bf16_f32 v6, v6, s0
	v_cvt_pk_bf16_f32 v7, v7, s0
	ds_write_b16 v12, v6
	ds_write_b16 v12, v7 offset:128
	global_load_dwordx2 v[210:211], v18, s[2:3] offset:2048
	v_add_u32_e32 v12, s10, v12
	ds_read_u16 v9, v12
	ds_read_u16 v10, v12 offset:128
	s_waitcnt vmcnt(15)
	s_waitcnt lgkmcnt(1)
	v_lshlrev_b32_e32 v9, 16, v9
	s_waitcnt lgkmcnt(0)
	v_lshlrev_b32_e32 v10, 16, v10
	v_mul_f32_e32 v11, v213, v10
	v_mul_f32_e32 v10, v212, v10
	v_fma_f32 v6, v212, v9, -v11
	v_fmac_f32_e32 v10, v213, v9
	v_mul_f32_e32 v6, v3, v6
	v_mul_f32_e32 v7, v3, v10
	v_cvt_pk_bf16_f32 v6, v6, s0
	v_cvt_pk_bf16_f32 v7, v7, s0
	ds_write_b16 v12, v6
	ds_write_b16 v12, v7 offset:128
	v_add_u32_e32 v19, 0x8000, v19
	global_load_dwordx2 v[212:213], v19, s[2:3]
	v_add_u32_e32 v12, s10, v12
	ds_read_u16 v9, v12
	ds_read_u16 v10, v12 offset:128
	s_waitcnt vmcnt(15)
	s_waitcnt lgkmcnt(1)
	v_lshlrev_b32_e32 v9, 16, v9
	s_waitcnt lgkmcnt(0)
	v_lshlrev_b32_e32 v10, 16, v10
	v_mul_f32_e32 v11, v215, v10
	v_mul_f32_e32 v10, v214, v10
	v_fma_f32 v6, v214, v9, -v11
	v_fmac_f32_e32 v10, v215, v9
	v_mul_f32_e32 v6, v3, v6
	v_mul_f32_e32 v7, v3, v10
	v_cvt_pk_bf16_f32 v6, v6, s0
	v_cvt_pk_bf16_f32 v7, v7, s0
	ds_write_b16 v12, v6
	ds_write_b16 v12, v7 offset:128
	global_load_dwordx2 v[214:215], v19, s[2:3] offset:2048
	v_add_u32_e32 v12, s10, v12
	ds_read_u16 v9, v12
	ds_read_u16 v10, v12 offset:128
	s_waitcnt vmcnt(15)
	s_waitcnt lgkmcnt(1)
	v_lshlrev_b32_e32 v9, 16, v9
	s_waitcnt lgkmcnt(0)
	v_lshlrev_b32_e32 v10, 16, v10
	v_mul_f32_e32 v11, v217, v10
	v_mul_f32_e32 v10, v216, v10
	v_fma_f32 v6, v216, v9, -v11
	v_fmac_f32_e32 v10, v217, v9
	v_mul_f32_e32 v6, v3, v6
	v_mul_f32_e32 v7, v3, v10
	v_cvt_pk_bf16_f32 v6, v6, s0
	v_cvt_pk_bf16_f32 v7, v7, s0
	ds_write_b16 v12, v6
	ds_write_b16 v12, v7 offset:128
	v_add_u32_e32 v20, 0x8000, v20
	global_load_dwordx2 v[216:217], v20, s[2:3]
	v_add_u32_e32 v12, s10, v12
	ds_read_u16 v9, v12
	ds_read_u16 v10, v12 offset:128
	s_waitcnt vmcnt(15)
	s_waitcnt lgkmcnt(1)
	v_lshlrev_b32_e32 v9, 16, v9
	s_waitcnt lgkmcnt(0)
	v_lshlrev_b32_e32 v10, 16, v10
	v_mul_f32_e32 v11, v219, v10
	v_mul_f32_e32 v10, v218, v10
	v_fma_f32 v6, v218, v9, -v11
	v_fmac_f32_e32 v10, v219, v9
	v_mul_f32_e32 v6, v3, v6
	v_mul_f32_e32 v7, v3, v10
	v_cvt_pk_bf16_f32 v6, v6, s0
	v_cvt_pk_bf16_f32 v7, v7, s0
	ds_write_b16 v12, v6
	ds_write_b16 v12, v7 offset:128
	global_load_dwordx2 v[218:219], v20, s[2:3] offset:2048
	v_add_u32_e32 v12, s10, v12
	ds_read_u16 v9, v12
	ds_read_u16 v10, v12 offset:128
	s_waitcnt vmcnt(15)
	s_waitcnt lgkmcnt(1)
	v_lshlrev_b32_e32 v9, 16, v9
	s_waitcnt lgkmcnt(0)
	v_lshlrev_b32_e32 v10, 16, v10
	v_mul_f32_e32 v11, v221, v10
	v_mul_f32_e32 v10, v220, v10
	v_fma_f32 v6, v220, v9, -v11
	v_fmac_f32_e32 v10, v221, v9
	v_mul_f32_e32 v6, v3, v6
	v_mul_f32_e32 v7, v3, v10
	v_cvt_pk_bf16_f32 v6, v6, s0
	v_cvt_pk_bf16_f32 v7, v7, s0
	ds_write_b16 v12, v6
	ds_write_b16 v12, v7 offset:128
	v_add_u32_e32 v21, 0x8000, v21
	global_load_dwordx2 v[220:221], v21, s[2:3]
	v_add_u32_e32 v12, s10, v12
	ds_read_u16 v9, v12
	ds_read_u16 v10, v12 offset:128
	s_waitcnt vmcnt(15)
; DI float bf2f(bf16_t v) { return __uint_as_float(((unsigned)v) << 16); }
; DI bf16_t f2bf(float x) { return (bf16_t)(pack2(x, 0.f) & 0xffffu); }
; DI int tid512() { int t = threadIdx_x_raw(); asm volatile("" : "+v"(t)); return t; }
;   DI void operator()(bf16_t* sCb) const {
;     ...
;     if (nt2 < 4) {
;       const float2* rope = (const float2*)(ws + OFF_ROPER);
;       const float sc = (nt2 >= 2) ? 0.08838834764831845f : 1.f;
;       for (int id = tid512(); id < 256 * 128; id += 512) {
;         int row = id >> 7, hf = (id >> 6) & 1, i = id & 63;
;         float2 cs = rope[(size_t)(s0 + row) * 64 + i];
;         bf16_t* q1 = sCb + row * BLD + 128 * hf + i;
;         float x1 = bf2f(q1[0]), x2 = bf2f(q1[64]);
;         q1[0] = f2bf((x1 * cs.x - x2 * cs.y) * sc);
;         q1[64] = f2bf((x1 * cs.y + x2 * cs.x) * sc);
;       }
;       __syncthreads();
	s_waitcnt lgkmcnt(1)
	v_lshlrev_b32_e32 v9, 16, v9
	s_waitcnt lgkmcnt(0)
	v_lshlrev_b32_e32 v10, 16, v10
	v_mul_f32_e32 v11, v223, v10
	v_mul_f32_e32 v10, v222, v10
	v_fma_f32 v6, v222, v9, -v11
	v_fmac_f32_e32 v10, v223, v9
	v_mul_f32_e32 v6, v3, v6
	v_mul_f32_e32 v7, v3, v10
	v_cvt_pk_bf16_f32 v6, v6, s0
	v_cvt_pk_bf16_f32 v7, v7, s0
	ds_write_b16 v12, v6
	ds_write_b16 v12, v7 offset:128
	global_load_dwordx2 v[222:223], v21, s[2:3] offset:2048
	v_add_u32_e32 v12, s10, v12
	ds_read_u16 v9, v12
	ds_read_u16 v10, v12 offset:128
	s_waitcnt vmcnt(15)
	s_waitcnt lgkmcnt(1)
	v_lshlrev_b32_e32 v9, 16, v9
	s_waitcnt lgkmcnt(0)
	v_lshlrev_b32_e32 v10, 16, v10
	v_mul_f32_e32 v11, v225, v10
	v_mul_f32_e32 v10, v224, v10
	v_fma_f32 v6, v224, v9, -v11
	v_fmac_f32_e32 v10, v225, v9
	v_mul_f32_e32 v6, v3, v6
	v_mul_f32_e32 v7, v3, v10
	v_cvt_pk_bf16_f32 v6, v6, s0
	v_cvt_pk_bf16_f32 v7, v7, s0
	ds_write_b16 v12, v6
	ds_write_b16 v12, v7 offset:128
	v_add_u32_e32 v22, 0x8000, v22
	global_load_dwordx2 v[224:225], v22, s[2:3]
	v_add_u32_e32 v12, s10, v12
	ds_read_u16 v9, v12
	ds_read_u16 v10, v12 offset:128
	s_waitcnt vmcnt(15)
	s_waitcnt lgkmcnt(1)
	v_lshlrev_b32_e32 v9, 16, v9
	s_waitcnt lgkmcnt(0)
	v_lshlrev_b32_e32 v10, 16, v10
	v_mul_f32_e32 v11, v227, v10
	v_mul_f32_e32 v10, v226, v10
	v_fma_f32 v6, v226, v9, -v11
	v_fmac_f32_e32 v10, v227, v9
	v_mul_f32_e32 v6, v3, v6
	v_mul_f32_e32 v7, v3, v10
	v_cvt_pk_bf16_f32 v6, v6, s0
	v_cvt_pk_bf16_f32 v7, v7, s0
	ds_write_b16 v12, v6
	ds_write_b16 v12, v7 offset:128
	global_load_dwordx2 v[226:227], v22, s[2:3] offset:2048
	v_add_u32_e32 v12, s10, v12
	ds_read_u16 v9, v12
	ds_read_u16 v10, v12 offset:128
	s_waitcnt vmcnt(15)
	s_waitcnt lgkmcnt(1)
	v_lshlrev_b32_e32 v9, 16, v9
	s_waitcnt lgkmcnt(0)
	v_lshlrev_b32_e32 v10, 16, v10
	v_mul_f32_e32 v11, v229, v10
	v_mul_f32_e32 v10, v228, v10
	v_fma_f32 v6, v228, v9, -v11
	v_fmac_f32_e32 v10, v229, v9
	v_mul_f32_e32 v6, v3, v6
	v_mul_f32_e32 v7, v3, v10
	v_cvt_pk_bf16_f32 v6, v6, s0
	v_cvt_pk_bf16_f32 v7, v7, s0
	ds_write_b16 v12, v6
	ds_write_b16 v12, v7 offset:128
	v_add_u32_e32 v23, 0x8000, v23
	global_load_dwordx2 v[228:229], v23, s[2:3]
	v_add_u32_e32 v12, s10, v12
	ds_read_u16 v9, v12
	ds_read_u16 v10, v12 offset:128
	s_waitcnt vmcnt(15)
	s_waitcnt lgkmcnt(1)
	v_lshlrev_b32_e32 v9, 16, v9
	s_waitcnt lgkmcnt(0)
	v_lshlrev_b32_e32 v10, 16, v10
	v_mul_f32_e32 v11, v231, v10
	v_mul_f32_e32 v10, v230, v10
	v_fma_f32 v6, v230, v9, -v11
	v_fmac_f32_e32 v10, v231, v9
	v_mul_f32_e32 v6, v3, v6
	v_mul_f32_e32 v7, v3, v10
	v_cvt_pk_bf16_f32 v6, v6, s0
	v_cvt_pk_bf16_f32 v7, v7, s0
	ds_write_b16 v12, v6
	ds_write_b16 v12, v7 offset:128
	global_load_dwordx2 v[230:231], v23, s[2:3] offset:2048
	v_add_u32_e32 v12, s10, v12
	ds_read_u16 v9, v12
	ds_read_u16 v10, v12 offset:128
	s_waitcnt vmcnt(15)
	s_waitcnt lgkmcnt(1)
	v_lshlrev_b32_e32 v9, 16, v9
	s_waitcnt lgkmcnt(0)
	v_lshlrev_b32_e32 v10, 16, v10
	v_mul_f32_e32 v11, v201, v10
	v_mul_f32_e32 v10, v200, v10
	v_fma_f32 v6, v200, v9, -v11
	v_fmac_f32_e32 v10, v201, v9
	v_mul_f32_e32 v6, v3, v6
	v_mul_f32_e32 v7, v3, v10
	v_cvt_pk_bf16_f32 v6, v6, s0
	v_cvt_pk_bf16_f32 v7, v7, s0
	ds_write_b16 v12, v6
	ds_write_b16 v12, v7 offset:128
	v_add_u32_e32 v16, 0x8000, v16
	global_load_dwordx2 v[200:201], v16, s[2:3]
	v_add_u32_e32 v12, s10, v12
	ds_read_u16 v9, v12
	ds_read_u16 v10, v12 offset:128
	s_waitcnt vmcnt(15)
	s_waitcnt lgkmcnt(1)
	v_lshlrev_b32_e32 v9, 16, v9
	s_waitcnt lgkmcnt(0)
	v_lshlrev_b32_e32 v10, 16, v10
	v_mul_f32_e32 v11, v203, v10
	v_mul_f32_e32 v10, v202, v10
	v_fma_f32 v6, v202, v9, -v11
	v_fmac_f32_e32 v10, v203, v9
	v_mul_f32_e32 v6, v3, v6
	v_mul_f32_e32 v7, v3, v10
	v_cvt_pk_bf16_f32 v6, v6, s0
	v_cvt_pk_bf16_f32 v7, v7, s0
	ds_write_b16 v12, v6
	ds_write_b16 v12, v7 offset:128
	global_load_dwordx2 v[202:203], v16, s[2:3] offset:2048
	v_add_u32_e32 v12, s10, v12
	ds_read_u16 v9, v12
	ds_read_u16 v10, v12 offset:128
	s_waitcnt vmcnt(15)
	s_waitcnt lgkmcnt(1)
	v_lshlrev_b32_e32 v9, 16, v9
	s_waitcnt lgkmcnt(0)
	v_lshlrev_b32_e32 v10, 16, v10
	v_mul_f32_e32 v11, v205, v10
	v_mul_f32_e32 v10, v204, v10
	v_fma_f32 v6, v204, v9, -v11
	v_fmac_f32_e32 v10, v205, v9
	v_mul_f32_e32 v6, v3, v6
	v_mul_f32_e32 v7, v3, v10
	v_cvt_pk_bf16_f32 v6, v6, s0
	v_cvt_pk_bf16_f32 v7, v7, s0
	ds_write_b16 v12, v6
	ds_write_b16 v12, v7 offset:128
	v_add_u32_e32 v17, 0x8000, v17
	global_load_dwordx2 v[204:205], v17, s[2:3]
	v_add_u32_e32 v12, s10, v12
	ds_read_u16 v9, v12
	ds_read_u16 v10, v12 offset:128
	s_waitcnt vmcnt(15)
	s_waitcnt lgkmcnt(1)
	v_lshlrev_b32_e32 v9, 16, v9
	s_waitcnt lgkmcnt(0)
	v_lshlrev_b32_e32 v10, 16, v10
	v_mul_f32_e32 v11, v207, v10
	v_mul_f32_e32 v10, v206, v10
	v_fma_f32 v6, v206, v9, -v11
	v_fmac_f32_e32 v10, v207, v9
	v_mul_f32_e32 v6, v3, v6
	v_mul_f32_e32 v7, v3, v10
	v_cvt_pk_bf16_f32 v6, v6, s0
	v_cvt_pk_bf16_f32 v7, v7, s0
	ds_write_b16 v12, v6
	ds_write_b16 v12, v7 offset:128
	global_load_dwordx2 v[206:207], v17, s[2:3] offset:2048
	v_add_u32_e32 v12, s10, v12
	ds_read_u16 v9, v12
	ds_read_u16 v10, v12 offset:128
	s_waitcnt vmcnt(15)
	s_waitcnt lgkmcnt(1)
	v_lshlrev_b32_e32 v9, 16, v9
	s_waitcnt lgkmcnt(0)
	v_lshlrev_b32_e32 v10, 16, v10
	v_mul_f32_e32 v11, v209, v10
	v_mul_f32_e32 v10, v208, v10
	v_fma_f32 v6, v208, v9, -v11
	v_fmac_f32_e32 v10, v209, v9
	v_mul_f32_e32 v6, v3, v6
	v_mul_f32_e32 v7, v3, v10
	v_cvt_pk_bf16_f32 v6, v6, s0
	v_cvt_pk_bf16_f32 v7, v7, s0
	ds_write_b16 v12, v6
	ds_write_b16 v12, v7 offset:128
	v_add_u32_e32 v18, 0x8000, v18
	global_load_dwordx2 v[208:209], v18, s[2:3]
	v_add_u32_e32 v12, s10, v12
	ds_read_u16 v9, v12
	ds_read_u16 v10, v12 offset:128
	s_waitcnt vmcnt(15)
; DI float bf2f(bf16_t v) { return __uint_as_float(((unsigned)v) << 16); }
; DI bf16_t f2bf(float x) { return (bf16_t)(pack2(x, 0.f) & 0xffffu); }
; DI int tid512() { int t = threadIdx_x_raw(); asm volatile("" : "+v"(t)); return t; }
;   DI void operator()(bf16_t* sCb) const {
;     ...
;       for (int id = tid512(); id < 256 * 128; id += 512) {
;         int row = id >> 7, hf = (id >> 6) & 1, i = id & 63;
;         float2 cs = rope[(size_t)(s0 + row) * 64 + i];
;         bf16_t* q1 = sCb + row * BLD + 128 * hf + i;
;         float x1 = bf2f(q1[0]), x2 = bf2f(q1[64]);
;         q1[0] = f2bf((x1 * cs.x - x2 * cs.y) * sc);
;         q1[64] = f2bf((x1 * cs.y + x2 * cs.x) * sc);
;       }
	s_waitcnt lgkmcnt(1)
	v_lshlrev_b32_e32 v9, 16, v9
	s_waitcnt lgkmcnt(0)
	v_lshlrev_b32_e32 v10, 16, v10
	v_mul_f32_e32 v11, v211, v10
	v_mul_f32_e32 v10, v210, v10
	v_fma_f32 v6, v210, v9, -v11
	v_fmac_f32_e32 v10, v211, v9
	v_mul_f32_e32 v6, v3, v6
	v_mul_f32_e32 v7, v3, v10
	v_cvt_pk_bf16_f32 v6, v6, s0
	v_cvt_pk_bf16_f32 v7, v7, s0
	ds_write_b16 v12, v6
	ds_write_b16 v12, v7 offset:128
	global_load_dwordx2 v[210:211], v18, s[2:3] offset:2048
	v_add_u32_e32 v12, s10, v12
	ds_read_u16 v9, v12
	ds_read_u16 v10, v12 offset:128
	s_waitcnt vmcnt(15)
	s_waitcnt lgkmcnt(1)
	v_lshlrev_b32_e32 v9, 16, v9
	s_waitcnt lgkmcnt(0)
	v_lshlrev_b32_e32 v10, 16, v10
	v_mul_f32_e32 v11, v213, v10
	v_mul_f32_e32 v10, v212, v10
	v_fma_f32 v6, v212, v9, -v11
	v_fmac_f32_e32 v10, v213, v9
	v_mul_f32_e32 v6, v3, v6
	v_mul_f32_e32 v7, v3, v10
	v_cvt_pk_bf16_f32 v6, v6, s0
	v_cvt_pk_bf16_f32 v7, v7, s0
	ds_write_b16 v12, v6
	ds_write_b16 v12, v7 offset:128
	v_add_u32_e32 v19, 0x8000, v19
	global_load_dwordx2 v[212:213], v19, s[2:3]
	v_add_u32_e32 v12, s10, v12
	ds_read_u16 v9, v12
	ds_read_u16 v10, v12 offset:128
	s_waitcnt vmcnt(15)
	s_waitcnt lgkmcnt(1)
	v_lshlrev_b32_e32 v9, 16, v9
	s_waitcnt lgkmcnt(0)
	v_lshlrev_b32_e32 v10, 16, v10
	v_mul_f32_e32 v11, v215, v10
	v_mul_f32_e32 v10, v214, v10
	v_fma_f32 v6, v214, v9, -v11
	v_fmac_f32_e32 v10, v215, v9
	v_mul_f32_e32 v6, v3, v6
	v_mul_f32_e32 v7, v3, v10
	v_cvt_pk_bf16_f32 v6, v6, s0
	v_cvt_pk_bf16_f32 v7, v7, s0
	ds_write_b16 v12, v6
	ds_write_b16 v12, v7 offset:128
	global_load_dwordx2 v[214:215], v19, s[2:3] offset:2048
	v_add_u32_e32 v12, s10, v12
	ds_read_u16 v9, v12
	ds_read_u16 v10, v12 offset:128
	s_waitcnt vmcnt(15)
	s_waitcnt lgkmcnt(1)
	v_lshlrev_b32_e32 v9, 16, v9
	s_waitcnt lgkmcnt(0)
	v_lshlrev_b32_e32 v10, 16, v10
	v_mul_f32_e32 v11, v217, v10
	v_mul_f32_e32 v10, v216, v10
	v_fma_f32 v6, v216, v9, -v11
	v_fmac_f32_e32 v10, v217, v9
	v_mul_f32_e32 v6, v3, v6
	v_mul_f32_e32 v7, v3, v10
	v_cvt_pk_bf16_f32 v6, v6, s0
	v_cvt_pk_bf16_f32 v7, v7, s0
	ds_write_b16 v12, v6
	ds_write_b16 v12, v7 offset:128
	v_add_u32_e32 v20, 0x8000, v20
	global_load_dwordx2 v[216:217], v20, s[2:3]
	v_add_u32_e32 v12, s10, v12
	ds_read_u16 v9, v12
	ds_read_u16 v10, v12 offset:128
	s_waitcnt vmcnt(15)
	s_waitcnt lgkmcnt(1)
	v_lshlrev_b32_e32 v9, 16, v9
	s_waitcnt lgkmcnt(0)
	v_lshlrev_b32_e32 v10, 16, v10
	v_mul_f32_e32 v11, v219, v10
	v_mul_f32_e32 v10, v218, v10
	v_fma_f32 v6, v218, v9, -v11
	v_fmac_f32_e32 v10, v219, v9
	v_mul_f32_e32 v6, v3, v6
	v_mul_f32_e32 v7, v3, v10
	v_cvt_pk_bf16_f32 v6, v6, s0
	v_cvt_pk_bf16_f32 v7, v7, s0
	ds_write_b16 v12, v6
	ds_write_b16 v12, v7 offset:128
	global_load_dwordx2 v[218:219], v20, s[2:3] offset:2048
	v_add_u32_e32 v12, s10, v12
	ds_read_u16 v9, v12
	ds_read_u16 v10, v12 offset:128
	s_waitcnt vmcnt(15)
	s_waitcnt lgkmcnt(1)
	v_lshlrev_b32_e32 v9, 16, v9
	s_waitcnt lgkmcnt(0)
	v_lshlrev_b32_e32 v10, 16, v10
	v_mul_f32_e32 v11, v221, v10
	v_mul_f32_e32 v10, v220, v10
	v_fma_f32 v6, v220, v9, -v11
	v_fmac_f32_e32 v10, v221, v9
	v_mul_f32_e32 v6, v3, v6
	v_mul_f32_e32 v7, v3, v10
	v_cvt_pk_bf16_f32 v6, v6, s0
	v_cvt_pk_bf16_f32 v7, v7, s0
	ds_write_b16 v12, v6
	ds_write_b16 v12, v7 offset:128
	v_add_u32_e32 v21, 0x8000, v21
	global_load_dwordx2 v[220:221], v21, s[2:3]
	v_add_u32_e32 v12, s10, v12
	ds_read_u16 v9, v12
	ds_read_u16 v10, v12 offset:128
	s_waitcnt vmcnt(15)
	s_waitcnt lgkmcnt(1)
	v_lshlrev_b32_e32 v9, 16, v9
	s_waitcnt lgkmcnt(0)
	v_lshlrev_b32_e32 v10, 16, v10
	v_mul_f32_e32 v11, v223, v10
	v_mul_f32_e32 v10, v222, v10
	v_fma_f32 v6, v222, v9, -v11
	v_fmac_f32_e32 v10, v223, v9
	v_mul_f32_e32 v6, v3, v6
	v_mul_f32_e32 v7, v3, v10
	v_cvt_pk_bf16_f32 v6, v6, s0
	v_cvt_pk_bf16_f32 v7, v7, s0
	ds_write_b16 v12, v6
	ds_write_b16 v12, v7 offset:128
	global_load_dwordx2 v[222:223], v21, s[2:3] offset:2048
	v_add_u32_e32 v12, s10, v12
	ds_read_u16 v9, v12
	ds_read_u16 v10, v12 offset:128
	s_waitcnt vmcnt(15)
	s_waitcnt lgkmcnt(1)
	v_lshlrev_b32_e32 v9, 16, v9
	s_waitcnt lgkmcnt(0)
	v_lshlrev_b32_e32 v10, 16, v10
	v_mul_f32_e32 v11, v225, v10
	v_mul_f32_e32 v10, v224, v10
	v_fma_f32 v6, v224, v9, -v11
	v_fmac_f32_e32 v10, v225, v9
	v_mul_f32_e32 v6, v3, v6
	v_mul_f32_e32 v7, v3, v10
	v_cvt_pk_bf16_f32 v6, v6, s0
	v_cvt_pk_bf16_f32 v7, v7, s0
	ds_write_b16 v12, v6
	ds_write_b16 v12, v7 offset:128
	v_add_u32_e32 v22, 0x8000, v22
	global_load_dwordx2 v[224:225], v22, s[2:3]
	v_add_u32_e32 v12, s10, v12
	ds_read_u16 v9, v12
	ds_read_u16 v10, v12 offset:128
	s_waitcnt vmcnt(15)
	s_waitcnt lgkmcnt(1)
	v_lshlrev_b32_e32 v9, 16, v9
	s_waitcnt lgkmcnt(0)
	v_lshlrev_b32_e32 v10, 16, v10
	v_mul_f32_e32 v11, v227, v10
	v_mul_f32_e32 v10, v226, v10
	v_fma_f32 v6, v226, v9, -v11
	v_fmac_f32_e32 v10, v227, v9
	v_mul_f32_e32 v6, v3, v6
	v_mul_f32_e32 v7, v3, v10
	v_cvt_pk_bf16_f32 v6, v6, s0
	v_cvt_pk_bf16_f32 v7, v7, s0
	ds_write_b16 v12, v6
	ds_write_b16 v12, v7 offset:128
	global_load_dwordx2 v[226:227], v22, s[2:3] offset:2048
	v_add_u32_e32 v12, s10, v12
	ds_read_u16 v9, v12
	ds_read_u16 v10, v12 offset:128
	s_waitcnt vmcnt(15)
	s_waitcnt lgkmcnt(1)
	v_lshlrev_b32_e32 v9, 16, v9
	s_waitcnt lgkmcnt(0)
	v_lshlrev_b32_e32 v10, 16, v10
	v_mul_f32_e32 v11, v229, v10
	v_mul_f32_e32 v10, v228, v10
	v_fma_f32 v6, v228, v9, -v11
	v_fmac_f32_e32 v10, v229, v9
	v_mul_f32_e32 v6, v3, v6
	v_mul_f32_e32 v7, v3, v10
	v_cvt_pk_bf16_f32 v6, v6, s0
	v_cvt_pk_bf16_f32 v7, v7, s0
	ds_write_b16 v12, v6
	ds_write_b16 v12, v7 offset:128
	v_add_u32_e32 v23, 0x8000, v23
	global_load_dwordx2 v[228:229], v23, s[2:3]
	v_add_u32_e32 v12, s10, v12
	ds_read_u16 v9, v12
	ds_read_u16 v10, v12 offset:128
	s_waitcnt vmcnt(15)
; DI float bf2f(bf16_t v) { return __uint_as_float(((unsigned)v) << 16); }
; DI bf16_t f2bf(float x) { return (bf16_t)(pack2(x, 0.f) & 0xffffu); }
; DI int tid512() { int t = threadIdx_x_raw(); asm volatile("" : "+v"(t)); return t; }
;   DI void operator()(bf16_t* sCb) const {
;     ...
;       for (int id = tid512(); id < 256 * 128; id += 512) {
;         int row = id >> 7, hf = (id >> 6) & 1, i = id & 63;
;         float2 cs = rope[(size_t)(s0 + row) * 64 + i];
;         bf16_t* q1 = sCb + row * BLD + 128 * hf + i;
;         float x1 = bf2f(q1[0]), x2 = bf2f(q1[64]);
;         q1[0] = f2bf((x1 * cs.x - x2 * cs.y) * sc);
;         q1[64] = f2bf((x1 * cs.y + x2 * cs.x) * sc);
;       }
	s_waitcnt lgkmcnt(1)
	v_lshlrev_b32_e32 v9, 16, v9
	s_waitcnt lgkmcnt(0)
	v_lshlrev_b32_e32 v10, 16, v10
	v_mul_f32_e32 v11, v231, v10
	v_mul_f32_e32 v10, v230, v10
	v_fma_f32 v6, v230, v9, -v11
	v_fmac_f32_e32 v10, v231, v9
	v_mul_f32_e32 v6, v3, v6
	v_mul_f32_e32 v7, v3, v10
	v_cvt_pk_bf16_f32 v6, v6, s0
	v_cvt_pk_bf16_f32 v7, v7, s0
	ds_write_b16 v12, v6
	ds_write_b16 v12, v7 offset:128
	global_load_dwordx2 v[230:231], v23, s[2:3] offset:2048
	v_add_u32_e32 v12, s10, v12
	ds_read_u16 v9, v12
	ds_read_u16 v10, v12 offset:128
	s_waitcnt vmcnt(15)
	s_waitcnt lgkmcnt(1)
	v_lshlrev_b32_e32 v9, 16, v9
	s_waitcnt lgkmcnt(0)
	v_lshlrev_b32_e32 v10, 16, v10
	v_mul_f32_e32 v11, v201, v10
	v_mul_f32_e32 v10, v200, v10
	v_fma_f32 v6, v200, v9, -v11
	v_fmac_f32_e32 v10, v201, v9
	v_mul_f32_e32 v6, v3, v6
	v_mul_f32_e32 v7, v3, v10
	v_cvt_pk_bf16_f32 v6, v6, s0
	v_cvt_pk_bf16_f32 v7, v7, s0
	ds_write_b16 v12, v6
	ds_write_b16 v12, v7 offset:128
	v_add_u32_e32 v12, s10, v12
	ds_read_u16 v9, v12
	ds_read_u16 v10, v12 offset:128
	s_waitcnt vmcnt(14)
	s_waitcnt lgkmcnt(1)
	v_lshlrev_b32_e32 v9, 16, v9
	s_waitcnt lgkmcnt(0)
	v_lshlrev_b32_e32 v10, 16, v10
	v_mul_f32_e32 v11, v203, v10
	v_mul_f32_e32 v10, v202, v10
	v_fma_f32 v6, v202, v9, -v11
	v_fmac_f32_e32 v10, v203, v9
	v_mul_f32_e32 v6, v3, v6
	v_mul_f32_e32 v7, v3, v10
	v_cvt_pk_bf16_f32 v6, v6, s0
	v_cvt_pk_bf16_f32 v7, v7, s0
	ds_write_b16 v12, v6
	ds_write_b16 v12, v7 offset:128
	v_add_u32_e32 v12, s10, v12
	ds_read_u16 v9, v12
	ds_read_u16 v10, v12 offset:128
	s_waitcnt vmcnt(13)
	s_waitcnt lgkmcnt(1)
	v_lshlrev_b32_e32 v9, 16, v9
	s_waitcnt lgkmcnt(0)
	v_lshlrev_b32_e32 v10, 16, v10
	v_mul_f32_e32 v11, v205, v10
	v_mul_f32_e32 v10, v204, v10
	v_fma_f32 v6, v204, v9, -v11
	v_fmac_f32_e32 v10, v205, v9
	v_mul_f32_e32 v6, v3, v6
	v_mul_f32_e32 v7, v3, v10
	v_cvt_pk_bf16_f32 v6, v6, s0
	v_cvt_pk_bf16_f32 v7, v7, s0
	ds_write_b16 v12, v6
	ds_write_b16 v12, v7 offset:128
	v_add_u32_e32 v12, s10, v12
	ds_read_u16 v9, v12
	ds_read_u16 v10, v12 offset:128
	s_waitcnt vmcnt(12)
	s_waitcnt lgkmcnt(1)
	v_lshlrev_b32_e32 v9, 16, v9
	s_waitcnt lgkmcnt(0)
	v_lshlrev_b32_e32 v10, 16, v10
	v_mul_f32_e32 v11, v207, v10
	v_mul_f32_e32 v10, v206, v10
	v_fma_f32 v6, v206, v9, -v11
	v_fmac_f32_e32 v10, v207, v9
	v_mul_f32_e32 v6, v3, v6
	v_mul_f32_e32 v7, v3, v10
	v_cvt_pk_bf16_f32 v6, v6, s0
	v_cvt_pk_bf16_f32 v7, v7, s0
	ds_write_b16 v12, v6
	ds_write_b16 v12, v7 offset:128
	v_add_u32_e32 v12, s10, v12
	ds_read_u16 v9, v12
	ds_read_u16 v10, v12 offset:128
	s_waitcnt vmcnt(11)
	s_waitcnt lgkmcnt(1)
	v_lshlrev_b32_e32 v9, 16, v9
	s_waitcnt lgkmcnt(0)
	v_lshlrev_b32_e32 v10, 16, v10
	v_mul_f32_e32 v11, v209, v10
	v_mul_f32_e32 v10, v208, v10
	v_fma_f32 v6, v208, v9, -v11
	v_fmac_f32_e32 v10, v209, v9
	v_mul_f32_e32 v6, v3, v6
	v_mul_f32_e32 v7, v3, v10
	v_cvt_pk_bf16_f32 v6, v6, s0
	v_cvt_pk_bf16_f32 v7, v7, s0
	ds_write_b16 v12, v6
	ds_write_b16 v12, v7 offset:128
	v_add_u32_e32 v12, s10, v12
	ds_read_u16 v9, v12
	ds_read_u16 v10, v12 offset:128
	s_waitcnt vmcnt(10)
	s_waitcnt lgkmcnt(1)
	v_lshlrev_b32_e32 v9, 16, v9
	s_waitcnt lgkmcnt(0)
	v_lshlrev_b32_e32 v10, 16, v10
	v_mul_f32_e32 v11, v211, v10
	v_mul_f32_e32 v10, v210, v10
	v_fma_f32 v6, v210, v9, -v11
	v_fmac_f32_e32 v10, v211, v9
	v_mul_f32_e32 v6, v3, v6
	v_mul_f32_e32 v7, v3, v10
	v_cvt_pk_bf16_f32 v6, v6, s0
	v_cvt_pk_bf16_f32 v7, v7, s0
	ds_write_b16 v12, v6
	ds_write_b16 v12, v7 offset:128
	v_add_u32_e32 v12, s10, v12
	ds_read_u16 v9, v12
	ds_read_u16 v10, v12 offset:128
	s_waitcnt vmcnt(9)
	s_waitcnt lgkmcnt(1)
	v_lshlrev_b32_e32 v9, 16, v9
	s_waitcnt lgkmcnt(0)
	v_lshlrev_b32_e32 v10, 16, v10
	v_mul_f32_e32 v11, v213, v10
	v_mul_f32_e32 v10, v212, v10
	v_fma_f32 v6, v212, v9, -v11
	v_fmac_f32_e32 v10, v213, v9
	v_mul_f32_e32 v6, v3, v6
	v_mul_f32_e32 v7, v3, v10
	v_cvt_pk_bf16_f32 v6, v6, s0
	v_cvt_pk_bf16_f32 v7, v7, s0
	ds_write_b16 v12, v6
	ds_write_b16 v12, v7 offset:128
	v_add_u32_e32 v12, s10, v12
	ds_read_u16 v9, v12
	ds_read_u16 v10, v12 offset:128
	s_waitcnt vmcnt(8)
	s_waitcnt lgkmcnt(1)
	v_lshlrev_b32_e32 v9, 16, v9
	s_waitcnt lgkmcnt(0)
; DI float bf2f(bf16_t v) { return __uint_as_float(((unsigned)v) << 16); }
; DI bf16_t f2bf(float x) { return (bf16_t)(pack2(x, 0.f) & 0xffffu); }
; DI int tid512() { int t = threadIdx_x_raw(); asm volatile("" : "+v"(t)); return t; }
;   DI void operator()(bf16_t* sCb) const {
;     ...
;       for (int id = tid512(); id < 256 * 128; id += 512) {
;         int row = id >> 7, hf = (id >> 6) & 1, i = id & 63;
;         float2 cs = rope[(size_t)(s0 + row) * 64 + i];
;         bf16_t* q1 = sCb + row * BLD + 128 * hf + i;
;         float x1 = bf2f(q1[0]), x2 = bf2f(q1[64]);
;         q1[0] = f2bf((x1 * cs.x - x2 * cs.y) * sc);
;         q1[64] = f2bf((x1 * cs.y + x2 * cs.x) * sc);
;       }
	v_lshlrev_b32_e32 v10, 16, v10
	v_mul_f32_e32 v11, v215, v10
	v_mul_f32_e32 v10, v214, v10
	v_fma_f32 v6, v214, v9, -v11
	v_fmac_f32_e32 v10, v215, v9
	v_mul_f32_e32 v6, v3, v6
	v_mul_f32_e32 v7, v3, v10
	v_cvt_pk_bf16_f32 v6, v6, s0
	v_cvt_pk_bf16_f32 v7, v7, s0
	ds_write_b16 v12, v6
	ds_write_b16 v12, v7 offset:128
	v_add_u32_e32 v12, s10, v12
	ds_read_u16 v9, v12
	ds_read_u16 v10, v12 offset:128
	s_waitcnt vmcnt(7)
	s_waitcnt lgkmcnt(1)
	v_lshlrev_b32_e32 v9, 16, v9
	s_waitcnt lgkmcnt(0)
	v_lshlrev_b32_e32 v10, 16, v10
	v_mul_f32_e32 v11, v217, v10
	v_mul_f32_e32 v10, v216, v10
	v_fma_f32 v6, v216, v9, -v11
	v_fmac_f32_e32 v10, v217, v9
	v_mul_f32_e32 v6, v3, v6
	v_mul_f32_e32 v7, v3, v10
	v_cvt_pk_bf16_f32 v6, v6, s0
	v_cvt_pk_bf16_f32 v7, v7, s0
	ds_write_b16 v12, v6
	ds_write_b16 v12, v7 offset:128
	v_add_u32_e32 v12, s10, v12
	ds_read_u16 v9, v12
	ds_read_u16 v10, v12 offset:128
	s_waitcnt vmcnt(6)
	s_waitcnt lgkmcnt(1)
	v_lshlrev_b32_e32 v9, 16, v9
	s_waitcnt lgkmcnt(0)
	v_lshlrev_b32_e32 v10, 16, v10
	v_mul_f32_e32 v11, v219, v10
	v_mul_f32_e32 v10, v218, v10
	v_fma_f32 v6, v218, v9, -v11
	v_fmac_f32_e32 v10, v219, v9
	v_mul_f32_e32 v6, v3, v6
	v_mul_f32_e32 v7, v3, v10
	v_cvt_pk_bf16_f32 v6, v6, s0
	v_cvt_pk_bf16_f32 v7, v7, s0
	ds_write_b16 v12, v6
	ds_write_b16 v12, v7 offset:128
	v_add_u32_e32 v12, s10, v12
	ds_read_u16 v9, v12
	ds_read_u16 v10, v12 offset:128
	s_waitcnt vmcnt(5)
	s_waitcnt lgkmcnt(1)
	v_lshlrev_b32_e32 v9, 16, v9
	s_waitcnt lgkmcnt(0)
	v_lshlrev_b32_e32 v10, 16, v10
	v_mul_f32_e32 v11, v221, v10
	v_mul_f32_e32 v10, v220, v10
	v_fma_f32 v6, v220, v9, -v11
	v_fmac_f32_e32 v10, v221, v9
	v_mul_f32_e32 v6, v3, v6
	v_mul_f32_e32 v7, v3, v10
	v_cvt_pk_bf16_f32 v6, v6, s0
	v_cvt_pk_bf16_f32 v7, v7, s0
	ds_write_b16 v12, v6
	ds_write_b16 v12, v7 offset:128
	v_add_u32_e32 v12, s10, v12
	ds_read_u16 v9, v12
	ds_read_u16 v10, v12 offset:128
	s_waitcnt vmcnt(4)
	s_waitcnt lgkmcnt(1)
	v_lshlrev_b32_e32 v9, 16, v9
	s_waitcnt lgkmcnt(0)
	v_lshlrev_b32_e32 v10, 16, v10
	v_mul_f32_e32 v11, v223, v10
	v_mul_f32_e32 v10, v222, v10
	v_fma_f32 v6, v222, v9, -v11
	v_fmac_f32_e32 v10, v223, v9
	v_mul_f32_e32 v6, v3, v6
	v_mul_f32_e32 v7, v3, v10
	v_cvt_pk_bf16_f32 v6, v6, s0
	v_cvt_pk_bf16_f32 v7, v7, s0
	ds_write_b16 v12, v6
	ds_write_b16 v12, v7 offset:128
	v_add_u32_e32 v12, s10, v12
	ds_read_u16 v9, v12
	ds_read_u16 v10, v12 offset:128
	s_waitcnt vmcnt(3)
	s_waitcnt lgkmcnt(1)
	v_lshlrev_b32_e32 v9, 16, v9
	s_waitcnt lgkmcnt(0)
	v_lshlrev_b32_e32 v10, 16, v10
	v_mul_f32_e32 v11, v225, v10
	v_mul_f32_e32 v10, v224, v10
	v_fma_f32 v6, v224, v9, -v11
	v_fmac_f32_e32 v10, v225, v9
	v_mul_f32_e32 v6, v3, v6
	v_mul_f32_e32 v7, v3, v10
	v_cvt_pk_bf16_f32 v6, v6, s0
	v_cvt_pk_bf16_f32 v7, v7, s0
	ds_write_b16 v12, v6
	ds_write_b16 v12, v7 offset:128
	v_add_u32_e32 v12, s10, v12
	ds_read_u16 v9, v12
	ds_read_u16 v10, v12 offset:128
	s_waitcnt vmcnt(2)
	s_waitcnt lgkmcnt(1)
	v_lshlrev_b32_e32 v9, 16, v9
	s_waitcnt lgkmcnt(0)
	v_lshlrev_b32_e32 v10, 16, v10
	v_mul_f32_e32 v11, v227, v10
	v_mul_f32_e32 v10, v226, v10
	v_fma_f32 v6, v226, v9, -v11
	v_fmac_f32_e32 v10, v227, v9
	v_mul_f32_e32 v6, v3, v6
	v_mul_f32_e32 v7, v3, v10
	v_cvt_pk_bf16_f32 v6, v6, s0
	v_cvt_pk_bf16_f32 v7, v7, s0
	ds_write_b16 v12, v6
	ds_write_b16 v12, v7 offset:128
	v_add_u32_e32 v12, s10, v12
	ds_read_u16 v9, v12
	ds_read_u16 v10, v12 offset:128
	s_waitcnt vmcnt(1)
	s_waitcnt lgkmcnt(1)
	v_lshlrev_b32_e32 v9, 16, v9
	s_waitcnt lgkmcnt(0)
	v_lshlrev_b32_e32 v10, 16, v10
	v_mul_f32_e32 v11, v229, v10
	v_mul_f32_e32 v10, v228, v10
	v_fma_f32 v6, v228, v9, -v11
	v_fmac_f32_e32 v10, v229, v9
	v_mul_f32_e32 v6, v3, v6
	v_mul_f32_e32 v7, v3, v10
	v_cvt_pk_bf16_f32 v6, v6, s0
	v_cvt_pk_bf16_f32 v7, v7, s0
	ds_write_b16 v12, v6
	ds_write_b16 v12, v7 offset:128
	v_add_u32_e32 v12, s10, v12
	ds_read_u16 v9, v12
	ds_read_u16 v10, v12 offset:128
	s_waitcnt vmcnt(0)
	s_waitcnt lgkmcnt(1)
	v_lshlrev_b32_e32 v9, 16, v9
	s_waitcnt lgkmcnt(0)
	v_lshlrev_b32_e32 v10, 16, v10
	v_mul_f32_e32 v11, v231, v10
	v_mul_f32_e32 v10, v230, v10
	v_fma_f32 v6, v230, v9, -v11
	v_fmac_f32_e32 v10, v231, v9
	v_mul_f32_e32 v6, v3, v6
	v_mul_f32_e32 v7, v3, v10
	v_cvt_pk_bf16_f32 v6, v6, s0
	v_cvt_pk_bf16_f32 v7, v7, s0
	ds_write_b16 v12, v6
	ds_write_b16 v12, v7 offset:128
	v_add_u32_e32 v12, s10, v12
